# A: v7 + EpiResid epilogues rewritten (swapped MFMA operands, dword row-contiguous loads/stores, batched)
# baseline (speedup 1.0000x reference)
; #define PG8_STAGE(bufoff, gbase, voff) do { _Pragma("unroll") for (int _i = 0; _i < 2; ++_i) \
;         __builtin_amdgcn_global_load_lds((const unsigned*)((const char*)(gbase) + (voff)[_i]), (PG8_LAS unsigned*)(lds + (bufoff) + ldsw + _i * 8192), 16, 0, 0); } while (0)
; #define PG8_LDA(dst, b, h) do { _Pragma("unroll") for (int m = 0; m < 4; ++m) _Pragma("unroll") for (int k = 0; k < 2; ++k) dst[m][k] = *(const PG8_LAS bf16x8*)(lds + PG8_SA(b, h) + aoff + m * 2048 + k * 1024); } while (0)
; #define PG8_LDB(dst, b, h) do { _Pragma("unroll") for (int n = 0; n < 2; ++n) _Pragma("unroll") for (int k = 0; k < 2; ++k) dst[n][k] = *(const PG8_LAS bf16x8*)(lds + PG8_SB(b, h) + boff + n * 2048 + k * 1024); } while (0)
; #define PG8_MMA(ai, bj, At, Bt) do { __builtin_amdgcn_s_setprio(1); _Pragma("unroll") for (int m = 0; m < 4; ++m) _Pragma("unroll") for (int n = 0; n < 2; ++n) _Pragma("unroll") for (int k = 0; k < 2; ++k) \
;         acc[ai][bj][m][n] = __builtin_amdgcn_mfma_f32_16x16x32_bf16(Bt[n][k], At[m][k], acc[ai][bj][m][n], 0, 0, 0); __builtin_amdgcn_s_setprio(0); } while (0)
; template <class Epi, class Sched, bool ALIGN_EPI = false, bool SP2 = false>
; __device__ __forceinline__ void gemm_phase(PG8_LAS unsigned char* lds, const Gemm g, const Sched& S, const Epi& E, int wave_s) {
;     ...
;         for (int t = 0; t < nt; t += 2) {
;             const bool last = (t == nt - 2);
;             const char* a1 = cA + (size_t)(t + 1) * kstep;
;             const char* a2 = last ? nA : cA + (size_t)(t + 2) * kstep; const char* b2 = last ? nB : cB + (size_t)(t + 2) * kstep;
;             const char* a3 = a2 + kstep; const char* b3 = b2 + kstep;
;             if (last && has_next) S.a_ready(nxt);
;             if constexpr (Epi::HAS_MID) { if (t == nt / 2) E.mid(acc, cur, wr, wc, fr, fq); }
;             if constexpr (SP2) {
;             PG8_LDB(B0, 0, 0); PG8_LDB(B1, 0, 1); PG8_SCHED; PG8_LDA(At, 0, 0); PG8_STAGE(PG8_SA(1, 1), a1 + hstepA, voffA);
;             PG8_WAIT_V(8); PG8_WAIT_L(0); PG8_BAR; PG8_MMA(0, 0, At, B0); PG8_MMA(0, 1, At, B1); PG8_BAR; PG8_SCHED;
;             PG8_LDA(At, 0, 1); PG8_STAGE(PG8_SB(0, 0), b2, voffB); PG8_STAGE(PG8_SB(0, 1), b2 + hstepB, voffB); PG8_STAGE(PG8_SA(0, 0), a2, voffA);
;             PG8_WAIT_V(8); PG8_WAIT_L(0); PG8_BAR; PG8_MMA(1, 0, At, B0); PG8_MMA(1, 1, At, B1); PG8_BAR; PG8_SCHED;
.LBB0_358:
	s_add_u32 s18, s16, 0x100
	s_addc_u32 s19, s17, 0
	s_add_i32 s34, 0, 0x10000
	s_cmpk_eq_i32 s41, 0x54
	s_cselect_b32 s25, s13, s19
	s_cselect_b32 s24, s12, s18
	s_cselect_b32 s21, s15, s40
	s_cselect_b32 s20, s14, s27
	s_add_i32 s35, 0, 0x14000
	v_add_u32_e32 v148, s34, v159
	v_add_u32_e32 v156, s35, v159
	ds_read_b128 v[136:139], v148
	ds_read_b128 v[140:143], v148 offset:1024
	ds_read_b128 v[144:147], v148 offset:2048
	ds_read_b128 v[148:151], v148 offset:3072
	ds_read_b128 v[152:155], v156
	ds_read_b128 v[162:165], v156 offset:1024
	ds_read_b128 v[166:169], v156 offset:2048
	ds_read_b128 v[176:179], v156 offset:3072
	v_lshl_add_u64 v[156:157], s[16:17], 0, v[134:135]
	s_add_i32 m0, s42, 0xc000
	ds_read_b128 v[180:183], v161
	ds_read_b128 v[184:187], v161 offset:1024
	ds_read_b128 v[188:191], v161 offset:2048
	ds_read_b128 v[192:195], v161 offset:3072
	ds_read_b128 v[196:199], v161 offset:4096
	ds_read_b128 v[208:211], v161 offset:5120
	ds_read_b128 v[212:215], v161 offset:6144
	ds_read_b128 v[216:219], v161 offset:7168
	global_load_lds_dwordx4 v[156:157], off
	v_lshl_add_u64 v[156:157], s[16:17], 0, v[132:133]
	s_add_i32 m0, s42, 0xe000
	s_nop 0
	global_load_lds_dwordx4 v[156:157], off
	s_waitcnt vmcnt(8)
	s_waitcnt lgkmcnt(0)
	s_barrier
	s_setprio 1
	s_waitcnt lgkmcnt(0)
	v_mfma_f32_16x16x32_bf16 v[126:129], v[180:183], v[136:139], v[126:129]
	v_mfma_f32_16x16x32_bf16 v[122:125], v[180:183], v[144:147], v[122:125]
	v_mfma_f32_16x16x32_bf16 v[110:113], v[188:191], v[136:139], v[110:113]
	v_mfma_f32_16x16x32_bf16 v[106:109], v[188:191], v[144:147], v[106:109]
	v_mfma_f32_16x16x32_bf16 v[94:97], v[196:199], v[136:139], v[94:97]
	v_mfma_f32_16x16x32_bf16 v[90:93], v[196:199], v[144:147], v[90:93]
	v_mfma_f32_16x16x32_bf16 v[78:81], v[212:215], v[136:139], v[78:81]
	v_mfma_f32_16x16x32_bf16 v[74:77], v[212:215], v[144:147], v[74:77]
	v_mfma_f32_16x16x32_bf16 v[126:129], v[184:187], v[140:143], v[126:129]
	v_mfma_f32_16x16x32_bf16 v[122:125], v[184:187], v[148:151], v[122:125]
	v_mfma_f32_16x16x32_bf16 v[110:113], v[192:195], v[140:143], v[110:113]
	v_mfma_f32_16x16x32_bf16 v[106:109], v[192:195], v[148:151], v[106:109]
	v_mfma_f32_16x16x32_bf16 v[94:97], v[208:211], v[140:143], v[94:97]
	v_mfma_f32_16x16x32_bf16 v[90:93], v[208:211], v[148:151], v[90:93]
	v_mfma_f32_16x16x32_bf16 v[78:81], v[216:219], v[140:143], v[78:81]
	v_mfma_f32_16x16x32_bf16 v[74:77], v[216:219], v[148:151], v[74:77]
	s_setprio 0
	s_setprio 1
	v_mfma_f32_16x16x32_bf16 v[118:121], v[180:183], v[152:155], v[118:121]
	v_mfma_f32_16x16x32_bf16 v[114:117], v[180:183], v[166:169], v[114:117]
	v_mfma_f32_16x16x32_bf16 v[102:105], v[188:191], v[152:155], v[102:105]
	v_mfma_f32_16x16x32_bf16 v[98:101], v[188:191], v[166:169], v[98:101]
	v_mfma_f32_16x16x32_bf16 v[86:89], v[196:199], v[152:155], v[86:89]
	v_mfma_f32_16x16x32_bf16 v[82:85], v[196:199], v[166:169], v[82:85]
	v_mfma_f32_16x16x32_bf16 v[70:73], v[212:215], v[152:155], v[70:73]
	v_mfma_f32_16x16x32_bf16 v[66:69], v[212:215], v[166:169], v[66:69]
	v_mfma_f32_16x16x32_bf16 v[118:121], v[184:187], v[162:165], v[118:121]
	v_mfma_f32_16x16x32_bf16 v[114:117], v[184:187], v[176:179], v[114:117]
	v_mfma_f32_16x16x32_bf16 v[102:105], v[192:195], v[162:165], v[102:105]
	v_mfma_f32_16x16x32_bf16 v[98:101], v[192:195], v[176:179], v[98:101]
	v_mfma_f32_16x16x32_bf16 v[86:89], v[208:211], v[162:165], v[86:89]
	v_mfma_f32_16x16x32_bf16 v[82:85], v[208:211], v[176:179], v[82:85]
	v_mfma_f32_16x16x32_bf16 v[70:73], v[216:219], v[162:165], v[70:73]
	v_mfma_f32_16x16x32_bf16 v[66:69], v[216:219], v[176:179], v[66:69]
	s_setprio 0
	s_barrier
	s_add_i32 s16, s34, s37
	v_lshl_add_u64 v[156:157], s[20:21], 0, v[0:1]
	s_mov_b32 m0, s16
	ds_read_b128 v[180:183], v161 offset:16384
	ds_read_b128 v[184:187], v161 offset:17408
	ds_read_b128 v[188:191], v161 offset:18432
	ds_read_b128 v[192:195], v161 offset:19456
	ds_read_b128 v[196:199], v161 offset:20480
	ds_read_b128 v[208:211], v161 offset:21504
	ds_read_b128 v[212:215], v161 offset:22528
	ds_read_b128 v[216:219], v161 offset:23552
	global_load_lds_dwordx4 v[156:157], off
	s_add_i32 m0, s16, 0x2000
	s_add_u32 s16, s20, 0x160000
	v_lshl_add_u64 v[170:171], s[20:21], 0, v[130:131]
	s_addc_u32 s17, s21, 0
	s_add_i32 s34, s35, s37
	global_load_lds_dwordx4 v[170:171], off
	v_lshl_add_u64 v[200:201], s[16:17], 0, v[0:1]
	s_mov_b32 m0, s34
	v_lshl_add_u64 v[220:221], s[24:25], 0, v[130:131]
	global_load_lds_dwordx4 v[200:201], off
	v_lshl_add_u64 v[200:201], s[16:17], 0, v[130:131]
	s_add_i32 m0, s34, 0x2000
	s_nop 0
	global_load_lds_dwordx4 v[200:201], off
	v_lshl_add_u64 v[200:201], s[24:25], 0, v[0:1]
	s_mov_b32 m0, s42
	s_nop 0
	global_load_lds_dwordx4 v[200:201], off
	s_mov_b32 m0, s43
	s_nop 0
	global_load_lds_dwordx4 v[220:221], off
	s_waitcnt vmcnt(8)
	s_waitcnt lgkmcnt(0)
	s_barrier
; #define PG8_STAGE(bufoff, gbase, voff) do { _Pragma("unroll") for (int _i = 0; _i < 2; ++_i) \
;         __builtin_amdgcn_global_load_lds((const unsigned*)((const char*)(gbase) + (voff)[_i]), (PG8_LAS unsigned*)(lds + (bufoff) + ldsw + _i * 8192), 16, 0, 0); } while (0)
; #define PG8_LDA(dst, b, h) do { _Pragma("unroll") for (int m = 0; m < 4; ++m) _Pragma("unroll") for (int k = 0; k < 2; ++k) dst[m][k] = *(const PG8_LAS bf16x8*)(lds + PG8_SA(b, h) + aoff + m * 2048 + k * 1024); } while (0)
; #define PG8_LDB(dst, b, h) do { _Pragma("unroll") for (int n = 0; n < 2; ++n) _Pragma("unroll") for (int k = 0; k < 2; ++k) dst[n][k] = *(const PG8_LAS bf16x8*)(lds + PG8_SB(b, h) + boff + n * 2048 + k * 1024); } while (0)
; #define PG8_MMA(ai, bj, At, Bt) do { __builtin_amdgcn_s_setprio(1); _Pragma("unroll") for (int m = 0; m < 4; ++m) _Pragma("unroll") for (int n = 0; n < 2; ++n) _Pragma("unroll") for (int k = 0; k < 2; ++k) \
;         acc[ai][bj][m][n] = __builtin_amdgcn_mfma_f32_16x16x32_bf16(Bt[n][k], At[m][k], acc[ai][bj][m][n], 0, 0, 0); __builtin_amdgcn_s_setprio(0); } while (0)
; #define PG8_WAIT_V(n) asm volatile("s_waitcnt vmcnt(" #n ")" ::: "memory")
; #define PG8_WAIT_L(n) asm volatile("s_waitcnt lgkmcnt(" #n ")" ::: "memory")
; #define PG8_BAR __builtin_amdgcn_s_barrier()
; #define PG8_SCHED __builtin_amdgcn_sched_barrier(0)
; template <class Epi, class Sched, bool ALIGN_EPI = false, bool SP2 = false>
; __device__ __forceinline__ void gemm_phase(PG8_LAS unsigned char* lds, const Gemm g, const Sched& S, const Epi& E, int wave_s) {
;     ...
;             PG8_WAIT_V(8); PG8_WAIT_L(0); PG8_BAR; PG8_MMA(1, 0, At, B0); PG8_MMA(1, 1, At, B1); PG8_BAR; PG8_SCHED;
;             PG8_LDB(B0, 1, 0); PG8_LDB(B1, 1, 1); PG8_SCHED; PG8_LDA(At, 1, 0); PG8_STAGE(PG8_SA(0, 1), a2 + hstepA, voffA);
;             PG8_WAIT_V(8); PG8_WAIT_L(0); PG8_BAR; PG8_MMA(0, 0, At, B0); PG8_MMA(0, 1, At, B1); PG8_BAR; PG8_SCHED;
;             PG8_LDA(At, 1, 1); PG8_STAGE(PG8_SB(1, 0), b3, voffB); PG8_STAGE(PG8_SB(1, 1), b3 + hstepB, voffB); PG8_STAGE(PG8_SA(1, 0), a3, voffA);
	s_setprio 1
	s_waitcnt lgkmcnt(0)
	v_mfma_f32_16x16x32_bf16 v[62:65], v[180:183], v[136:139], v[62:65]
	v_mfma_f32_16x16x32_bf16 v[58:61], v[180:183], v[144:147], v[58:61]
	v_mfma_f32_16x16x32_bf16 v[46:49], v[188:191], v[136:139], v[46:49]
	v_mfma_f32_16x16x32_bf16 v[42:45], v[188:191], v[144:147], v[42:45]
	v_mfma_f32_16x16x32_bf16 v[30:33], v[196:199], v[136:139], v[30:33]
	v_mfma_f32_16x16x32_bf16 v[26:29], v[196:199], v[144:147], v[26:29]
	v_mfma_f32_16x16x32_bf16 v[14:17], v[212:215], v[136:139], v[14:17]
	v_mfma_f32_16x16x32_bf16 v[10:13], v[212:215], v[144:147], v[10:13]
	v_mfma_f32_16x16x32_bf16 v[62:65], v[184:187], v[140:143], v[62:65]
	v_mfma_f32_16x16x32_bf16 v[58:61], v[184:187], v[148:151], v[58:61]
	v_mfma_f32_16x16x32_bf16 v[46:49], v[192:195], v[140:143], v[46:49]
	v_mfma_f32_16x16x32_bf16 v[42:45], v[192:195], v[148:151], v[42:45]
	v_mfma_f32_16x16x32_bf16 v[30:33], v[208:211], v[140:143], v[30:33]
	v_mfma_f32_16x16x32_bf16 v[26:29], v[208:211], v[148:151], v[26:29]
	v_mfma_f32_16x16x32_bf16 v[14:17], v[216:219], v[140:143], v[14:17]
	v_mfma_f32_16x16x32_bf16 v[10:13], v[216:219], v[148:151], v[10:13]
	s_setprio 0
	s_setprio 1
	v_mfma_f32_16x16x32_bf16 v[54:57], v[180:183], v[152:155], v[54:57]
	v_mfma_f32_16x16x32_bf16 v[50:53], v[180:183], v[166:169], v[50:53]
	v_mfma_f32_16x16x32_bf16 v[38:41], v[188:191], v[152:155], v[38:41]
	v_mfma_f32_16x16x32_bf16 v[34:37], v[188:191], v[166:169], v[34:37]
	v_mfma_f32_16x16x32_bf16 v[22:25], v[196:199], v[152:155], v[22:25]
	v_mfma_f32_16x16x32_bf16 v[18:21], v[196:199], v[166:169], v[18:21]
	v_mfma_f32_16x16x32_bf16 v[6:9], v[212:215], v[152:155], v[6:9]
	v_mfma_f32_16x16x32_bf16 v[2:5], v[212:215], v[166:169], v[2:5]
	v_mfma_f32_16x16x32_bf16 v[54:57], v[184:187], v[162:165], v[54:57]
	v_mfma_f32_16x16x32_bf16 v[50:53], v[184:187], v[176:179], v[50:53]
	v_mfma_f32_16x16x32_bf16 v[38:41], v[192:195], v[162:165], v[38:41]
	v_mfma_f32_16x16x32_bf16 v[34:37], v[192:195], v[176:179], v[34:37]
	v_mfma_f32_16x16x32_bf16 v[22:25], v[208:211], v[162:165], v[22:25]
	v_mfma_f32_16x16x32_bf16 v[18:21], v[208:211], v[176:179], v[18:21]
	v_mfma_f32_16x16x32_bf16 v[6:9], v[216:219], v[162:165], v[6:9]
	v_mfma_f32_16x16x32_bf16 v[2:5], v[216:219], v[176:179], v[2:5]
	s_setprio 0
	s_barrier
	s_add_i32 s34, 0, 0x18000
	s_add_i32 s35, 0, 0x1c000
	v_add_u32_e32 v148, s34, v159
	v_add_u32_e32 v176, s35, v159
	ds_read_b128 v[136:139], v148
	ds_read_b128 v[140:143], v148 offset:1024
	ds_read_b128 v[144:147], v148 offset:2048
	ds_read_b128 v[148:151], v148 offset:3072
	ds_read_b128 v[152:155], v176
	ds_read_b128 v[162:165], v176 offset:1024
	ds_read_b128 v[166:169], v176 offset:2048
	ds_read_b128 v[176:179], v176 offset:3072
	s_add_u32 s16, s24, 0x160000
	s_addc_u32 s17, s25, 0
	s_mov_b32 m0, s44
	v_lshl_add_u64 v[222:223], s[16:17], 0, v[0:1]
	ds_read_b128 v[180:183], v161 offset:32768
	ds_read_b128 v[184:187], v161 offset:33792
	ds_read_b128 v[188:191], v161 offset:34816
	ds_read_b128 v[192:195], v161 offset:35840
	ds_read_b128 v[196:199], v161 offset:36864
	ds_read_b128 v[208:211], v161 offset:37888
	ds_read_b128 v[212:215], v161 offset:38912
	ds_read_b128 v[216:219], v161 offset:39936
	global_load_lds_dwordx4 v[222:223], off
	v_lshl_add_u64 v[222:223], s[16:17], 0, v[130:131]
	s_mov_b32 m0, s45
	s_nop 0
	global_load_lds_dwordx4 v[222:223], off
	s_waitcnt vmcnt(8)
	s_waitcnt lgkmcnt(0)
	s_barrier
	s_setprio 1
	s_waitcnt lgkmcnt(0)
	v_mfma_f32_16x16x32_bf16 v[126:129], v[180:183], v[136:139], v[126:129]
	v_mfma_f32_16x16x32_bf16 v[122:125], v[180:183], v[144:147], v[122:125]
	v_mfma_f32_16x16x32_bf16 v[110:113], v[188:191], v[136:139], v[110:113]
	v_mfma_f32_16x16x32_bf16 v[106:109], v[188:191], v[144:147], v[106:109]
	v_mfma_f32_16x16x32_bf16 v[94:97], v[196:199], v[136:139], v[94:97]
	v_mfma_f32_16x16x32_bf16 v[90:93], v[196:199], v[144:147], v[90:93]
	v_mfma_f32_16x16x32_bf16 v[78:81], v[212:215], v[136:139], v[78:81]
	v_mfma_f32_16x16x32_bf16 v[74:77], v[212:215], v[144:147], v[74:77]
	v_mfma_f32_16x16x32_bf16 v[126:129], v[184:187], v[140:143], v[126:129]
	v_mfma_f32_16x16x32_bf16 v[122:125], v[184:187], v[148:151], v[122:125]
	v_mfma_f32_16x16x32_bf16 v[110:113], v[192:195], v[140:143], v[110:113]
	v_mfma_f32_16x16x32_bf16 v[106:109], v[192:195], v[148:151], v[106:109]
	v_mfma_f32_16x16x32_bf16 v[94:97], v[208:211], v[140:143], v[94:97]
	v_mfma_f32_16x16x32_bf16 v[90:93], v[208:211], v[148:151], v[90:93]
	v_mfma_f32_16x16x32_bf16 v[78:81], v[216:219], v[140:143], v[78:81]
	v_mfma_f32_16x16x32_bf16 v[74:77], v[216:219], v[148:151], v[74:77]
	s_setprio 0
	s_setprio 1
	v_mfma_f32_16x16x32_bf16 v[118:121], v[180:183], v[152:155], v[118:121]
	v_mfma_f32_16x16x32_bf16 v[114:117], v[180:183], v[166:169], v[114:117]
	v_mfma_f32_16x16x32_bf16 v[102:105], v[188:191], v[152:155], v[102:105]
	v_mfma_f32_16x16x32_bf16 v[98:101], v[188:191], v[166:169], v[98:101]
	v_mfma_f32_16x16x32_bf16 v[86:89], v[196:199], v[152:155], v[86:89]
	v_mfma_f32_16x16x32_bf16 v[82:85], v[196:199], v[166:169], v[82:85]
	v_mfma_f32_16x16x32_bf16 v[70:73], v[212:215], v[152:155], v[70:73]
	v_mfma_f32_16x16x32_bf16 v[66:69], v[212:215], v[166:169], v[66:69]
	v_mfma_f32_16x16x32_bf16 v[118:121], v[184:187], v[162:165], v[118:121]
	v_mfma_f32_16x16x32_bf16 v[114:117], v[184:187], v[176:179], v[114:117]
	v_mfma_f32_16x16x32_bf16 v[102:105], v[192:195], v[162:165], v[102:105]
	v_mfma_f32_16x16x32_bf16 v[98:101], v[192:195], v[176:179], v[98:101]
	v_mfma_f32_16x16x32_bf16 v[86:89], v[208:211], v[162:165], v[86:89]
	v_mfma_f32_16x16x32_bf16 v[82:85], v[208:211], v[176:179], v[82:85]
	v_mfma_f32_16x16x32_bf16 v[70:73], v[216:219], v[162:165], v[70:73]
	v_mfma_f32_16x16x32_bf16 v[66:69], v[216:219], v[176:179], v[66:69]
	s_setprio 0
	s_barrier
; #define PG8_STAGE(bufoff, gbase, voff) do { _Pragma("unroll") for (int _i = 0; _i < 2; ++_i) \
;         __builtin_amdgcn_global_load_lds((const unsigned*)((const char*)(gbase) + (voff)[_i]), (PG8_LAS unsigned*)(lds + (bufoff) + ldsw + _i * 8192), 16, 0, 0); } while (0)
; #define PG8_LDA(dst, b, h) do { _Pragma("unroll") for (int m = 0; m < 4; ++m) _Pragma("unroll") for (int k = 0; k < 2; ++k) dst[m][k] = *(const PG8_LAS bf16x8*)(lds + PG8_SA(b, h) + aoff + m * 2048 + k * 1024); } while (0)
; #define PG8_WAIT_V(n) asm volatile("s_waitcnt vmcnt(" #n ")" ::: "memory")
; #define PG8_WAIT_L(n) asm volatile("s_waitcnt lgkmcnt(" #n ")" ::: "memory")
; #define PG8_BAR __builtin_amdgcn_s_barrier()
; #define PG8_SCHED __builtin_amdgcn_sched_barrier(0)
; template <class Epi, class Sched, bool ALIGN_EPI = false, bool SP2 = false>
; __device__ __forceinline__ void gemm_phase(PG8_LAS unsigned char* lds, const Gemm g, const Sched& S, const Epi& E, int wave_s) {
;     ...
;             PG8_LDA(At, 1, 1); PG8_STAGE(PG8_SB(1, 0), b3, voffB); PG8_STAGE(PG8_SB(1, 1), b3 + hstepB, voffB); PG8_STAGE(PG8_SA(1, 0), a3, voffA);
;             PG8_WAIT_V(8); PG8_WAIT_L(0); PG8_BAR; PG8_MMA(1, 0, At, B0); PG8_MMA(1, 1, At, B1); PG8_BAR; PG8_SCHED;
;     __device__ __forceinline__ void operator()(const pg8::f32x4 (&acc)[2][2][4][2], const pg8::Unit& u, int wr, int wc, int fr, int fq) const {
;         const int b = u.pm >> 4;
;         const int row0 = u.pm * 256 + wr * 64 + fr, col0 = u.pn * 256 + wc * 32 + 4 * fq;
;         pg8::f32x4 gv[2][2];
; #pragma unroll
;         for (int bj = 0; bj < 2; ++bj)
; #pragma unroll
;             for (int n = 0; n < 2; ++n) gv[bj][n] = *(const pg8::f32x4*)(gate + (size_t)b * NMOD + col0 + bj * 128 + n * 16) * coef;
; #pragma unroll
;         for (int ai = 0; ai < 2; ++ai)
; #pragma unroll
;             for (int m = 0; m < 4; ++m) { const size_t off = (size_t)(row0 + ai * 128 + m * 16) * D + col0;
; #pragma unroll
;                 for (int bj = 0; bj < 2; ++bj)
; #pragma unroll
;                     for (int n = 0; n < 2; ++n) { const pg8::f32x4 xv = *(const pg8::f32x4*)(xin + off + bj * 128 + n * 16);
;                         *(pg8::f32x4*)(xout + off + bj * 128 + n * 16) = xv + gv[bj][n] * acc[ai][bj][m][n]; }
;                 if (m & 1) asm volatile("" ::: "memory"); }
	s_add_i32 s16, s34, s37
	v_lshl_add_u64 v[156:157], v[156:157], 0, s[30:31]
	s_mov_b32 m0, s16
	ds_read_b128 v[180:183], v161 offset:49152
	ds_read_b128 v[184:187], v161 offset:50176
	ds_read_b128 v[188:191], v161 offset:51200
	ds_read_b128 v[192:195], v161 offset:52224
	ds_read_b128 v[196:199], v161 offset:53248
	ds_read_b128 v[208:211], v161 offset:54272
	ds_read_b128 v[212:215], v161 offset:55296
	ds_read_b128 v[216:219], v161 offset:56320
	global_load_lds_dwordx4 v[156:157], off
	s_add_i32 m0, s16, 0x2000
	s_add_u32 s16, s20, 0x160080
	v_lshl_add_u64 v[156:157], v[170:171], 0, s[30:31]
	s_addc_u32 s17, s21, 0
	s_add_i32 s20, s35, s37
	global_load_lds_dwordx4 v[156:157], off
	v_lshl_add_u64 v[156:157], s[16:17], 0, v[0:1]
	s_mov_b32 m0, s20
	s_nop 0
	global_load_lds_dwordx4 v[156:157], off
	v_lshl_add_u64 v[156:157], s[16:17], 0, v[130:131]
	s_add_i32 m0, s20, 0x2000
	s_nop 0
	global_load_lds_dwordx4 v[156:157], off
	v_lshl_add_u64 v[156:157], v[200:201], 0, s[30:31]
	s_mov_b32 m0, s48
	s_nop 0
	global_load_lds_dwordx4 v[156:157], off
	v_lshl_add_u64 v[156:157], v[220:221], 0, s[30:31]
	s_mov_b32 m0, s49
	s_nop 0
	global_load_lds_dwordx4 v[156:157], off
	s_waitcnt vmcnt(8)
	s_waitcnt lgkmcnt(0)
	s_barrier
	s_setprio 1
	s_waitcnt lgkmcnt(0)
	v_mfma_f32_16x16x32_bf16 v[62:65], v[180:183], v[136:139], v[62:65]
	v_mfma_f32_16x16x32_bf16 v[58:61], v[180:183], v[144:147], v[58:61]
	v_mfma_f32_16x16x32_bf16 v[46:49], v[188:191], v[136:139], v[46:49]
	v_mfma_f32_16x16x32_bf16 v[42:45], v[188:191], v[144:147], v[42:45]
	v_mfma_f32_16x16x32_bf16 v[30:33], v[196:199], v[136:139], v[30:33]
	v_mfma_f32_16x16x32_bf16 v[26:29], v[196:199], v[144:147], v[26:29]
	v_mfma_f32_16x16x32_bf16 v[14:17], v[212:215], v[136:139], v[14:17]
	v_mfma_f32_16x16x32_bf16 v[10:13], v[212:215], v[144:147], v[10:13]
	v_mfma_f32_16x16x32_bf16 v[62:65], v[184:187], v[140:143], v[62:65]
	v_mfma_f32_16x16x32_bf16 v[58:61], v[184:187], v[148:151], v[58:61]
	v_mfma_f32_16x16x32_bf16 v[46:49], v[192:195], v[140:143], v[46:49]
	v_mfma_f32_16x16x32_bf16 v[42:45], v[192:195], v[148:151], v[42:45]
	v_mfma_f32_16x16x32_bf16 v[30:33], v[208:211], v[140:143], v[30:33]
	v_mfma_f32_16x16x32_bf16 v[26:29], v[208:211], v[148:151], v[26:29]
	v_mfma_f32_16x16x32_bf16 v[14:17], v[216:219], v[140:143], v[14:17]
	v_mfma_f32_16x16x32_bf16 v[10:13], v[216:219], v[148:151], v[10:13]
	s_setprio 0
	s_setprio 1
	v_mfma_f32_16x16x32_bf16 v[54:57], v[180:183], v[152:155], v[54:57]
	v_mfma_f32_16x16x32_bf16 v[50:53], v[180:183], v[166:169], v[50:53]
	v_mfma_f32_16x16x32_bf16 v[38:41], v[188:191], v[152:155], v[38:41]
	v_mfma_f32_16x16x32_bf16 v[34:37], v[188:191], v[166:169], v[34:37]
	v_mfma_f32_16x16x32_bf16 v[22:25], v[196:199], v[152:155], v[22:25]
	v_mfma_f32_16x16x32_bf16 v[18:21], v[196:199], v[166:169], v[18:21]
	v_mfma_f32_16x16x32_bf16 v[6:9], v[212:215], v[152:155], v[6:9]
	v_mfma_f32_16x16x32_bf16 v[2:5], v[212:215], v[166:169], v[2:5]
	v_mfma_f32_16x16x32_bf16 v[54:57], v[184:187], v[162:165], v[54:57]
	v_mfma_f32_16x16x32_bf16 v[50:53], v[184:187], v[176:179], v[50:53]
	v_mfma_f32_16x16x32_bf16 v[38:41], v[192:195], v[162:165], v[38:41]
	v_mfma_f32_16x16x32_bf16 v[34:37], v[192:195], v[176:179], v[34:37]
	v_mfma_f32_16x16x32_bf16 v[22:25], v[208:211], v[162:165], v[22:25]
	v_mfma_f32_16x16x32_bf16 v[18:21], v[208:211], v[176:179], v[18:21]
	v_mfma_f32_16x16x32_bf16 v[6:9], v[216:219], v[162:165], v[6:9]
	v_mfma_f32_16x16x32_bf16 v[2:5], v[216:219], v[176:179], v[2:5]
	s_setprio 0
	s_barrier
	s_add_i32 s41, s41, 2
	s_add_u32 s27, s27, 0x100
	s_addc_u32 s40, s40, 0
	s_cmpk_gt_u32 s41, 0x55
	s_mov_b64 s[16:17], s[18:19]
	s_cbranch_scc0 .LBB0_358
	s_and_b64 vcc, exec, s[10:11]
	s_cbranch_vccz .LBB0_361
	s_barrier
.LBB0_361:
	v_and_b32_e32 v136, 0x40, v158
	v_and_b32_e32 v137, 12, v160
	v_or_b32_e32 v136, v136, v137
	v_and_b32_e32 v137, 0x60, v160
	v_and_or_b32 v137, v158, 15, v137
	v_lshlrev_b32_e32 v137, 2, v137
	v_lshl_add_u32 v136, v136, 13, v137
	s_ashr_i32 vcc_hi, s55, 4
	s_mul_i32 vcc_hi, vcc_hi, 0x12000
	s_lshl_b32 vcc_lo, s26, 10
	s_add_u32 vcc_hi, vcc_hi, vcc_lo
	s_add_u32 s16, s46, vcc_hi
	s_addc_u32 s17, s47, 0
	global_load_dword v138, v137, s[16:17]
	global_load_dword v139, v137, s[16:17] offset:64
	global_load_dword v140, v137, s[16:17] offset:512
	global_load_dword v141, v137, s[16:17] offset:576
	s_lshl_b32 vcc_hi, s55, 21
	s_add_u32 vcc_lo, vcc_lo, vcc_hi
	s_add_u32 s100, s0, vcc_lo
	s_addc_u32 s101, s1, 0
	s_add_u32 s16, s8, vcc_lo
	s_addc_u32 s17, s9, 0
	global_load_dword v142, v136, s[100:101]
	global_load_dword v143, v136, s[100:101] offset:64
	global_load_dword v144, v136, s[100:101] offset:512
	global_load_dword v145, v136, s[100:101] offset:576
	s_add_u32 s100, s100, 0x2000
	s_addc_u32 s101, s101, 0
	global_load_dword v146, v136, s[100:101]
	global_load_dword v147, v136, s[100:101] offset:64
	global_load_dword v148, v136, s[100:101] offset:512
	global_load_dword v149, v136, s[100:101] offset:576
	s_add_u32 s100, s100, 0x2000
	s_addc_u32 s101, s101, 0
	global_load_dword v150, v136, s[100:101]
	global_load_dword v151, v136, s[100:101] offset:64
	global_load_dword v152, v136, s[100:101] offset:512
	global_load_dword v153, v136, s[100:101] offset:576
	s_add_u32 s100, s100, 0x2000
	s_addc_u32 s101, s101, 0
	global_load_dword v154, v136, s[100:101]
	global_load_dword v155, v136, s[100:101] offset:64
	global_load_dword v162, v136, s[100:101] offset:512
	global_load_dword v163, v136, s[100:101] offset:576
	s_add_u32 s100, s100, 0x1a000
	s_addc_u32 s101, s101, 0
	global_load_dword v164, v136, s[100:101]
	global_load_dword v165, v136, s[100:101] offset:64
	global_load_dword v166, v136, s[100:101] offset:512
	global_load_dword v167, v136, s[100:101] offset:576
	s_add_u32 s100, s100, 0x2000
	s_addc_u32 s101, s101, 0
	global_load_dword v168, v136, s[100:101]
	global_load_dword v169, v136, s[100:101] offset:64
	global_load_dword v176, v136, s[100:101] offset:512
	global_load_dword v177, v136, s[100:101] offset:576
	s_add_u32 s100, s100, 0x2000
	s_addc_u32 s101, s101, 0
	global_load_dword v178, v136, s[100:101]
	global_load_dword v179, v136, s[100:101] offset:64
	global_load_dword v180, v136, s[100:101] offset:512
	global_load_dword v181, v136, s[100:101] offset:576
	s_add_u32 s100, s100, 0x2000
	s_addc_u32 s101, s101, 0
	global_load_dword v182, v136, s[100:101]
	global_load_dword v183, v136, s[100:101] offset:64
	global_load_dword v184, v136, s[100:101] offset:512
	global_load_dword v185, v136, s[100:101] offset:576
	s_add_u32 s100, s100, 0x1a000
	s_addc_u32 s101, s101, 0
	s_waitcnt vmcnt(16)
;     __device__ __forceinline__ void operator()(const pg8::f32x4 (&acc)[2][2][4][2], const pg8::Unit& u, int wr, int wc, int fr, int fq) const {
;     ...
;             for (int n = 0; n < 2; ++n) gv[bj][n] = *(const pg8::f32x4*)(gate + (size_t)b * NMOD + col0 + bj * 128 + n * 16) * coef;
; #pragma unroll
;         for (int ai = 0; ai < 2; ++ai)
; #pragma unroll
;             for (int m = 0; m < 4; ++m) { const size_t off = (size_t)(row0 + ai * 128 + m * 16) * D + col0;
; #pragma unroll
;                 for (int bj = 0; bj < 2; ++bj)
; #pragma unroll
;                     for (int n = 0; n < 2; ++n) { const pg8::f32x4 xv = *(const pg8::f32x4*)(xin + off + bj * 128 + n * 16);
;                         *(pg8::f32x4*)(xout + off + bj * 128 + n * 16) = xv + gv[bj][n] * acc[ai][bj][m][n]; }
;                 if (m & 1) asm volatile("" ::: "memory"); }
	v_mul_f32_e32 v138, 0.5, v138
	v_mul_f32_e32 v139, 0.5, v139
	v_mul_f32_e32 v140, 0.5, v140
	v_mul_f32_e32 v141, 0.5, v141
	v_fma_f32 v126, v126, v138, v142
	v_fma_f32 v122, v122, v139, v143
	v_fma_f32 v118, v118, v140, v144
	v_fma_f32 v114, v114, v141, v145
	v_fma_f32 v127, v127, v138, v146
	v_fma_f32 v123, v123, v139, v147
	v_fma_f32 v119, v119, v140, v148
	v_fma_f32 v115, v115, v141, v149
	v_fma_f32 v128, v128, v138, v150
	v_fma_f32 v124, v124, v139, v151
	v_fma_f32 v120, v120, v140, v152
	v_fma_f32 v116, v116, v141, v153
	v_fma_f32 v129, v129, v138, v154
	v_fma_f32 v125, v125, v139, v155
	v_fma_f32 v121, v121, v140, v162
	v_fma_f32 v117, v117, v141, v163
	global_store_dword v136, v126, s[16:17]
	global_store_dword v136, v122, s[16:17] offset:64
	global_store_dword v136, v118, s[16:17] offset:512
	global_store_dword v136, v114, s[16:17] offset:576
	s_add_u32 s16, s16, 0x2000
	s_addc_u32 s17, s17, 0
	global_store_dword v136, v127, s[16:17]
	global_store_dword v136, v123, s[16:17] offset:64
	global_store_dword v136, v119, s[16:17] offset:512
	global_store_dword v136, v115, s[16:17] offset:576
	s_add_u32 s16, s16, 0x2000
	s_addc_u32 s17, s17, 0
	global_store_dword v136, v128, s[16:17]
	global_store_dword v136, v124, s[16:17] offset:64
	global_store_dword v136, v120, s[16:17] offset:512
	global_store_dword v136, v116, s[16:17] offset:576
	s_add_u32 s16, s16, 0x2000
	s_addc_u32 s17, s17, 0
	global_store_dword v136, v129, s[16:17]
	global_store_dword v136, v125, s[16:17] offset:64
	global_store_dword v136, v121, s[16:17] offset:512
	global_store_dword v136, v117, s[16:17] offset:576
	s_add_u32 s16, s16, 0x1a000
	s_addc_u32 s17, s17, 0
	global_load_dword v142, v136, s[100:101]
	global_load_dword v143, v136, s[100:101] offset:64
	global_load_dword v144, v136, s[100:101] offset:512
	global_load_dword v145, v136, s[100:101] offset:576
	s_add_u32 s100, s100, 0x2000
	s_addc_u32 s101, s101, 0
	global_load_dword v146, v136, s[100:101]
	global_load_dword v147, v136, s[100:101] offset:64
	global_load_dword v148, v136, s[100:101] offset:512
	global_load_dword v149, v136, s[100:101] offset:576
	s_add_u32 s100, s100, 0x2000
	s_addc_u32 s101, s101, 0
	global_load_dword v150, v136, s[100:101]
	global_load_dword v151, v136, s[100:101] offset:64
	global_load_dword v152, v136, s[100:101] offset:512
	global_load_dword v153, v136, s[100:101] offset:576
	s_add_u32 s100, s100, 0x2000
	s_addc_u32 s101, s101, 0
	global_load_dword v154, v136, s[100:101]
	global_load_dword v155, v136, s[100:101] offset:64
	global_load_dword v162, v136, s[100:101] offset:512
	global_load_dword v163, v136, s[100:101] offset:576
	s_add_u32 s100, s100, 0x1a000
	s_addc_u32 s101, s101, 0
	s_waitcnt vmcnt(32)
	v_fma_f32 v110, v110, v138, v164
	v_fma_f32 v106, v106, v139, v165
	v_fma_f32 v102, v102, v140, v166
	v_fma_f32 v98, v98, v141, v167
	v_fma_f32 v111, v111, v138, v168
	v_fma_f32 v107, v107, v139, v169
	v_fma_f32 v103, v103, v140, v176
	v_fma_f32 v99, v99, v141, v177
	v_fma_f32 v112, v112, v138, v178
	v_fma_f32 v108, v108, v139, v179
	v_fma_f32 v104, v104, v140, v180
	v_fma_f32 v100, v100, v141, v181
	v_fma_f32 v113, v113, v138, v182
	v_fma_f32 v109, v109, v139, v183
	v_fma_f32 v105, v105, v140, v184
	v_fma_f32 v101, v101, v141, v185
	global_store_dword v136, v110, s[16:17]
	global_store_dword v136, v106, s[16:17] offset:64
	global_store_dword v136, v102, s[16:17] offset:512
	global_store_dword v136, v98, s[16:17] offset:576
	s_add_u32 s16, s16, 0x2000
	s_addc_u32 s17, s17, 0
	global_store_dword v136, v111, s[16:17]
	global_store_dword v136, v107, s[16:17] offset:64
	global_store_dword v136, v103, s[16:17] offset:512
	global_store_dword v136, v99, s[16:17] offset:576
	s_add_u32 s16, s16, 0x2000
	s_addc_u32 s17, s17, 0
	global_store_dword v136, v112, s[16:17]
	global_store_dword v136, v108, s[16:17] offset:64
	global_store_dword v136, v104, s[16:17] offset:512
	global_store_dword v136, v100, s[16:17] offset:576
	s_add_u32 s16, s16, 0x2000
	s_addc_u32 s17, s17, 0
	global_store_dword v136, v113, s[16:17]
	global_store_dword v136, v109, s[16:17] offset:64
	global_store_dword v136, v105, s[16:17] offset:512
	global_store_dword v136, v101, s[16:17] offset:576
	s_add_u32 s16, s16, 0x1a000
	s_addc_u32 s17, s17, 0
	global_load_dword v164, v136, s[100:101]
	global_load_dword v165, v136, s[100:101] offset:64
	global_load_dword v166, v136, s[100:101] offset:512
	global_load_dword v167, v136, s[100:101] offset:576
	s_add_u32 s100, s100, 0x2000
	s_addc_u32 s101, s101, 0
	global_load_dword v168, v136, s[100:101]
	global_load_dword v169, v136, s[100:101] offset:64
	global_load_dword v176, v136, s[100:101] offset:512
	global_load_dword v177, v136, s[100:101] offset:576
	s_add_u32 s100, s100, 0x2000
	s_addc_u32 s101, s101, 0
	global_load_dword v178, v136, s[100:101]
	global_load_dword v179, v136, s[100:101] offset:64
	global_load_dword v180, v136, s[100:101] offset:512
	global_load_dword v181, v136, s[100:101] offset:576
	s_add_u32 s100, s100, 0x2000
	s_addc_u32 s101, s101, 0
	global_load_dword v182, v136, s[100:101]
	global_load_dword v183, v136, s[100:101] offset:64
	global_load_dword v184, v136, s[100:101] offset:512
	global_load_dword v185, v136, s[100:101] offset:576
	s_add_u32 s100, s100, 0x9a000
	s_addc_u32 s101, s101, 0
	s_waitcnt vmcnt(32)
;     __device__ __forceinline__ void operator()(const pg8::f32x4 (&acc)[2][2][4][2], const pg8::Unit& u, int wr, int wc, int fr, int fq) const {
;     ...
;             for (int n = 0; n < 2; ++n) gv[bj][n] = *(const pg8::f32x4*)(gate + (size_t)b * NMOD + col0 + bj * 128 + n * 16) * coef;
; #pragma unroll
;         for (int ai = 0; ai < 2; ++ai)
; #pragma unroll
;             for (int m = 0; m < 4; ++m) { const size_t off = (size_t)(row0 + ai * 128 + m * 16) * D + col0;
; #pragma unroll
;                 for (int bj = 0; bj < 2; ++bj)
; #pragma unroll
;                     for (int n = 0; n < 2; ++n) { const pg8::f32x4 xv = *(const pg8::f32x4*)(xin + off + bj * 128 + n * 16);
;                         *(pg8::f32x4*)(xout + off + bj * 128 + n * 16) = xv + gv[bj][n] * acc[ai][bj][m][n]; }
;                 if (m & 1) asm volatile("" ::: "memory"); }
	v_fma_f32 v94, v94, v138, v142
	v_fma_f32 v90, v90, v139, v143
	v_fma_f32 v86, v86, v140, v144
	v_fma_f32 v82, v82, v141, v145
	v_fma_f32 v95, v95, v138, v146
	v_fma_f32 v91, v91, v139, v147
	v_fma_f32 v87, v87, v140, v148
	v_fma_f32 v83, v83, v141, v149
	v_fma_f32 v96, v96, v138, v150
	v_fma_f32 v92, v92, v139, v151
	v_fma_f32 v88, v88, v140, v152
	v_fma_f32 v84, v84, v141, v153
	v_fma_f32 v97, v97, v138, v154
	v_fma_f32 v93, v93, v139, v155
	v_fma_f32 v89, v89, v140, v162
	v_fma_f32 v85, v85, v141, v163
	global_store_dword v136, v94, s[16:17]
	global_store_dword v136, v90, s[16:17] offset:64
	global_store_dword v136, v86, s[16:17] offset:512
	global_store_dword v136, v82, s[16:17] offset:576
	s_add_u32 s16, s16, 0x2000
	s_addc_u32 s17, s17, 0
	global_store_dword v136, v95, s[16:17]
	global_store_dword v136, v91, s[16:17] offset:64
	global_store_dword v136, v87, s[16:17] offset:512
	global_store_dword v136, v83, s[16:17] offset:576
	s_add_u32 s16, s16, 0x2000
	s_addc_u32 s17, s17, 0
	global_store_dword v136, v96, s[16:17]
	global_store_dword v136, v92, s[16:17] offset:64
	global_store_dword v136, v88, s[16:17] offset:512
	global_store_dword v136, v84, s[16:17] offset:576
	s_add_u32 s16, s16, 0x2000
	s_addc_u32 s17, s17, 0
	global_store_dword v136, v97, s[16:17]
	global_store_dword v136, v93, s[16:17] offset:64
	global_store_dword v136, v89, s[16:17] offset:512
	global_store_dword v136, v85, s[16:17] offset:576
	s_add_u32 s16, s16, 0x1a000
	s_addc_u32 s17, s17, 0
	global_load_dword v142, v136, s[100:101]
	global_load_dword v143, v136, s[100:101] offset:64
	global_load_dword v144, v136, s[100:101] offset:512
	global_load_dword v145, v136, s[100:101] offset:576
	s_add_u32 s100, s100, 0x2000
	s_addc_u32 s101, s101, 0
	global_load_dword v146, v136, s[100:101]
	global_load_dword v147, v136, s[100:101] offset:64
	global_load_dword v148, v136, s[100:101] offset:512
	global_load_dword v149, v136, s[100:101] offset:576
	s_add_u32 s100, s100, 0x2000
	s_addc_u32 s101, s101, 0
	global_load_dword v150, v136, s[100:101]
	global_load_dword v151, v136, s[100:101] offset:64
	global_load_dword v152, v136, s[100:101] offset:512
	global_load_dword v153, v136, s[100:101] offset:576
	s_add_u32 s100, s100, 0x2000
	s_addc_u32 s101, s101, 0
	global_load_dword v154, v136, s[100:101]
	global_load_dword v155, v136, s[100:101] offset:64
	global_load_dword v162, v136, s[100:101] offset:512
	global_load_dword v163, v136, s[100:101] offset:576
	s_add_u32 s100, s100, 0x1a000
	s_addc_u32 s101, s101, 0
	s_waitcnt vmcnt(32)
	v_fma_f32 v78, v78, v138, v164
	v_fma_f32 v74, v74, v139, v165
	v_fma_f32 v70, v70, v140, v166
	v_fma_f32 v66, v66, v141, v167
	v_fma_f32 v79, v79, v138, v168
	v_fma_f32 v75, v75, v139, v169
	v_fma_f32 v71, v71, v140, v176
	v_fma_f32 v67, v67, v141, v177
	v_fma_f32 v80, v80, v138, v178
	v_fma_f32 v76, v76, v139, v179
	v_fma_f32 v72, v72, v140, v180
	v_fma_f32 v68, v68, v141, v181
	v_fma_f32 v81, v81, v138, v182
	v_fma_f32 v77, v77, v139, v183
	v_fma_f32 v73, v73, v140, v184
	v_fma_f32 v69, v69, v141, v185
	global_store_dword v136, v78, s[16:17]
	global_store_dword v136, v74, s[16:17] offset:64
	global_store_dword v136, v70, s[16:17] offset:512
	global_store_dword v136, v66, s[16:17] offset:576
	s_add_u32 s16, s16, 0x2000
	s_addc_u32 s17, s17, 0
	global_store_dword v136, v79, s[16:17]
	global_store_dword v136, v75, s[16:17] offset:64
	global_store_dword v136, v71, s[16:17] offset:512
	global_store_dword v136, v67, s[16:17] offset:576
	s_add_u32 s16, s16, 0x2000
	s_addc_u32 s17, s17, 0
	global_store_dword v136, v80, s[16:17]
	global_store_dword v136, v76, s[16:17] offset:64
	global_store_dword v136, v72, s[16:17] offset:512
	global_store_dword v136, v68, s[16:17] offset:576
	s_add_u32 s16, s16, 0x2000
	s_addc_u32 s17, s17, 0
	global_store_dword v136, v81, s[16:17]
	global_store_dword v136, v77, s[16:17] offset:64
	global_store_dword v136, v73, s[16:17] offset:512
	global_store_dword v136, v69, s[16:17] offset:576
	s_add_u32 s16, s16, 0x9a000
	s_addc_u32 s17, s17, 0
	global_load_dword v164, v136, s[100:101]
	global_load_dword v165, v136, s[100:101] offset:64
	global_load_dword v166, v136, s[100:101] offset:512
	global_load_dword v167, v136, s[100:101] offset:576
	s_add_u32 s100, s100, 0x2000
	s_addc_u32 s101, s101, 0
	global_load_dword v168, v136, s[100:101]
	global_load_dword v169, v136, s[100:101] offset:64
	global_load_dword v176, v136, s[100:101] offset:512
	global_load_dword v177, v136, s[100:101] offset:576
	s_add_u32 s100, s100, 0x2000
	s_addc_u32 s101, s101, 0
	global_load_dword v178, v136, s[100:101]
	global_load_dword v179, v136, s[100:101] offset:64
	global_load_dword v180, v136, s[100:101] offset:512
	global_load_dword v181, v136, s[100:101] offset:576
	s_add_u32 s100, s100, 0x2000
	s_addc_u32 s101, s101, 0
	global_load_dword v182, v136, s[100:101]
	global_load_dword v183, v136, s[100:101] offset:64
	global_load_dword v184, v136, s[100:101] offset:512
	global_load_dword v185, v136, s[100:101] offset:576
	s_add_u32 s100, s100, 0x1a000
	s_addc_u32 s101, s101, 0
	s_waitcnt vmcnt(32)
;     __device__ __forceinline__ void operator()(const pg8::f32x4 (&acc)[2][2][4][2], const pg8::Unit& u, int wr, int wc, int fr, int fq) const {
;     ...
;             for (int n = 0; n < 2; ++n) gv[bj][n] = *(const pg8::f32x4*)(gate + (size_t)b * NMOD + col0 + bj * 128 + n * 16) * coef;
; #pragma unroll
;         for (int ai = 0; ai < 2; ++ai)
; #pragma unroll
;             for (int m = 0; m < 4; ++m) { const size_t off = (size_t)(row0 + ai * 128 + m * 16) * D + col0;
; #pragma unroll
;                 for (int bj = 0; bj < 2; ++bj)
; #pragma unroll
;                     for (int n = 0; n < 2; ++n) { const pg8::f32x4 xv = *(const pg8::f32x4*)(xin + off + bj * 128 + n * 16);
;                         *(pg8::f32x4*)(xout + off + bj * 128 + n * 16) = xv + gv[bj][n] * acc[ai][bj][m][n]; }
;                 if (m & 1) asm volatile("" ::: "memory"); }
	v_fma_f32 v62, v62, v138, v142
	v_fma_f32 v58, v58, v139, v143
	v_fma_f32 v54, v54, v140, v144
	v_fma_f32 v50, v50, v141, v145
	v_fma_f32 v63, v63, v138, v146
	v_fma_f32 v59, v59, v139, v147
	v_fma_f32 v55, v55, v140, v148
	v_fma_f32 v51, v51, v141, v149
	v_fma_f32 v64, v64, v138, v150
	v_fma_f32 v60, v60, v139, v151
	v_fma_f32 v56, v56, v140, v152
	v_fma_f32 v52, v52, v141, v153
	v_fma_f32 v65, v65, v138, v154
	v_fma_f32 v61, v61, v139, v155
	v_fma_f32 v57, v57, v140, v162
	v_fma_f32 v53, v53, v141, v163
	global_store_dword v136, v62, s[16:17]
	global_store_dword v136, v58, s[16:17] offset:64
	global_store_dword v136, v54, s[16:17] offset:512
	global_store_dword v136, v50, s[16:17] offset:576
	s_add_u32 s16, s16, 0x2000
	s_addc_u32 s17, s17, 0
	global_store_dword v136, v63, s[16:17]
	global_store_dword v136, v59, s[16:17] offset:64
	global_store_dword v136, v55, s[16:17] offset:512
	global_store_dword v136, v51, s[16:17] offset:576
	s_add_u32 s16, s16, 0x2000
	s_addc_u32 s17, s17, 0
	global_store_dword v136, v64, s[16:17]
	global_store_dword v136, v60, s[16:17] offset:64
	global_store_dword v136, v56, s[16:17] offset:512
	global_store_dword v136, v52, s[16:17] offset:576
	s_add_u32 s16, s16, 0x2000
	s_addc_u32 s17, s17, 0
	global_store_dword v136, v65, s[16:17]
	global_store_dword v136, v61, s[16:17] offset:64
	global_store_dword v136, v57, s[16:17] offset:512
	global_store_dword v136, v53, s[16:17] offset:576
	s_add_u32 s16, s16, 0x1a000
	s_addc_u32 s17, s17, 0
	global_load_dword v142, v136, s[100:101]
	global_load_dword v143, v136, s[100:101] offset:64
	global_load_dword v144, v136, s[100:101] offset:512
	global_load_dword v145, v136, s[100:101] offset:576
	s_add_u32 s100, s100, 0x2000
	s_addc_u32 s101, s101, 0
	global_load_dword v146, v136, s[100:101]
	global_load_dword v147, v136, s[100:101] offset:64
	global_load_dword v148, v136, s[100:101] offset:512
	global_load_dword v149, v136, s[100:101] offset:576
	s_add_u32 s100, s100, 0x2000
	s_addc_u32 s101, s101, 0
	global_load_dword v150, v136, s[100:101]
	global_load_dword v151, v136, s[100:101] offset:64
	global_load_dword v152, v136, s[100:101] offset:512
	global_load_dword v153, v136, s[100:101] offset:576
	s_add_u32 s100, s100, 0x2000
	s_addc_u32 s101, s101, 0
	global_load_dword v154, v136, s[100:101]
	global_load_dword v155, v136, s[100:101] offset:64
	global_load_dword v162, v136, s[100:101] offset:512
	global_load_dword v163, v136, s[100:101] offset:576
	s_add_u32 s100, s100, 0x1a000
	s_addc_u32 s101, s101, 0
	s_waitcnt vmcnt(32)
	v_fma_f32 v46, v46, v138, v164
	v_fma_f32 v42, v42, v139, v165
	v_fma_f32 v38, v38, v140, v166
	v_fma_f32 v34, v34, v141, v167
	v_fma_f32 v47, v47, v138, v168
	v_fma_f32 v43, v43, v139, v169
	v_fma_f32 v39, v39, v140, v176
	v_fma_f32 v35, v35, v141, v177
	v_fma_f32 v48, v48, v138, v178
	v_fma_f32 v44, v44, v139, v179
	v_fma_f32 v40, v40, v140, v180
	v_fma_f32 v36, v36, v141, v181
	v_fma_f32 v49, v49, v138, v182
	v_fma_f32 v45, v45, v139, v183
	v_fma_f32 v41, v41, v140, v184
	v_fma_f32 v37, v37, v141, v185
	global_store_dword v136, v46, s[16:17]
	global_store_dword v136, v42, s[16:17] offset:64
	global_store_dword v136, v38, s[16:17] offset:512
	global_store_dword v136, v34, s[16:17] offset:576
	s_add_u32 s16, s16, 0x2000
	s_addc_u32 s17, s17, 0
	global_store_dword v136, v47, s[16:17]
	global_store_dword v136, v43, s[16:17] offset:64
	global_store_dword v136, v39, s[16:17] offset:512
	global_store_dword v136, v35, s[16:17] offset:576
	s_add_u32 s16, s16, 0x2000
	s_addc_u32 s17, s17, 0
	global_store_dword v136, v48, s[16:17]
	global_store_dword v136, v44, s[16:17] offset:64
	global_store_dword v136, v40, s[16:17] offset:512
	global_store_dword v136, v36, s[16:17] offset:576
	s_add_u32 s16, s16, 0x2000
	s_addc_u32 s17, s17, 0
	global_store_dword v136, v49, s[16:17]
	global_store_dword v136, v45, s[16:17] offset:64
	global_store_dword v136, v41, s[16:17] offset:512
	global_store_dword v136, v37, s[16:17] offset:576
	s_add_u32 s16, s16, 0x1a000
	s_addc_u32 s17, s17, 0
	global_load_dword v164, v136, s[100:101]
	global_load_dword v165, v136, s[100:101] offset:64
	global_load_dword v166, v136, s[100:101] offset:512
	global_load_dword v167, v136, s[100:101] offset:576
	s_add_u32 s100, s100, 0x2000
	s_addc_u32 s101, s101, 0
	global_load_dword v168, v136, s[100:101]
	global_load_dword v169, v136, s[100:101] offset:64
	global_load_dword v176, v136, s[100:101] offset:512
	global_load_dword v177, v136, s[100:101] offset:576
	s_add_u32 s100, s100, 0x2000
	s_addc_u32 s101, s101, 0
	global_load_dword v178, v136, s[100:101]
	global_load_dword v179, v136, s[100:101] offset:64
	global_load_dword v180, v136, s[100:101] offset:512
	global_load_dword v181, v136, s[100:101] offset:576
	s_add_u32 s100, s100, 0x2000
	s_addc_u32 s101, s101, 0
	global_load_dword v182, v136, s[100:101]
	global_load_dword v183, v136, s[100:101] offset:64
	global_load_dword v184, v136, s[100:101] offset:512
	global_load_dword v185, v136, s[100:101] offset:576
	s_waitcnt vmcnt(32)
;     __device__ __forceinline__ void operator()(const pg8::f32x4 (&acc)[2][2][4][2], const pg8::Unit& u, int wr, int wc, int fr, int fq) const {
;     ...
;             for (int n = 0; n < 2; ++n) gv[bj][n] = *(const pg8::f32x4*)(gate + (size_t)b * NMOD + col0 + bj * 128 + n * 16) * coef;
; #pragma unroll
;         for (int ai = 0; ai < 2; ++ai)
; #pragma unroll
;             for (int m = 0; m < 4; ++m) { const size_t off = (size_t)(row0 + ai * 128 + m * 16) * D + col0;
; #pragma unroll
;                 for (int bj = 0; bj < 2; ++bj)
; #pragma unroll
;                     for (int n = 0; n < 2; ++n) { const pg8::f32x4 xv = *(const pg8::f32x4*)(xin + off + bj * 128 + n * 16);
;                         *(pg8::f32x4*)(xout + off + bj * 128 + n * 16) = xv + gv[bj][n] * acc[ai][bj][m][n]; }
;                 if (m & 1) asm volatile("" ::: "memory"); }
	v_fma_f32 v30, v30, v138, v142
	v_fma_f32 v26, v26, v139, v143
	v_fma_f32 v22, v22, v140, v144
	v_fma_f32 v18, v18, v141, v145
	v_fma_f32 v31, v31, v138, v146
	v_fma_f32 v27, v27, v139, v147
	v_fma_f32 v23, v23, v140, v148
	v_fma_f32 v19, v19, v141, v149
	v_fma_f32 v32, v32, v138, v150
	v_fma_f32 v28, v28, v139, v151
	v_fma_f32 v24, v24, v140, v152
	v_fma_f32 v20, v20, v141, v153
	v_fma_f32 v33, v33, v138, v154
	v_fma_f32 v29, v29, v139, v155
	v_fma_f32 v25, v25, v140, v162
	v_fma_f32 v21, v21, v141, v163
	global_store_dword v136, v30, s[16:17]
	global_store_dword v136, v26, s[16:17] offset:64
	global_store_dword v136, v22, s[16:17] offset:512
	global_store_dword v136, v18, s[16:17] offset:576
	s_add_u32 s16, s16, 0x2000
	s_addc_u32 s17, s17, 0
	global_store_dword v136, v31, s[16:17]
	global_store_dword v136, v27, s[16:17] offset:64
	global_store_dword v136, v23, s[16:17] offset:512
	global_store_dword v136, v19, s[16:17] offset:576
	s_add_u32 s16, s16, 0x2000
	s_addc_u32 s17, s17, 0
	global_store_dword v136, v32, s[16:17]
	global_store_dword v136, v28, s[16:17] offset:64
	global_store_dword v136, v24, s[16:17] offset:512
	global_store_dword v136, v20, s[16:17] offset:576
	s_add_u32 s16, s16, 0x2000
	s_addc_u32 s17, s17, 0
	global_store_dword v136, v33, s[16:17]
	global_store_dword v136, v29, s[16:17] offset:64
	global_store_dword v136, v25, s[16:17] offset:512
	global_store_dword v136, v21, s[16:17] offset:576
	s_add_u32 s16, s16, 0x1a000
	s_addc_u32 s17, s17, 0
	s_waitcnt vmcnt(16)
	v_fma_f32 v14, v14, v138, v164
	v_fma_f32 v10, v10, v139, v165
	v_fma_f32 v6, v6, v140, v166
	v_fma_f32 v2, v2, v141, v167
	v_fma_f32 v15, v15, v138, v168
	v_fma_f32 v11, v11, v139, v169
	v_fma_f32 v7, v7, v140, v176
	v_fma_f32 v3, v3, v141, v177
	v_fma_f32 v16, v16, v138, v178
	v_fma_f32 v12, v12, v139, v179
	v_fma_f32 v8, v8, v140, v180
	v_fma_f32 v4, v4, v141, v181
	v_fma_f32 v17, v17, v138, v182
	v_fma_f32 v13, v13, v139, v183
	v_fma_f32 v9, v9, v140, v184
	v_fma_f32 v5, v5, v141, v185
	global_store_dword v136, v14, s[16:17]
	global_store_dword v136, v10, s[16:17] offset:64
	global_store_dword v136, v6, s[16:17] offset:512
	global_store_dword v136, v2, s[16:17] offset:576
	s_add_u32 s16, s16, 0x2000
	s_addc_u32 s17, s17, 0
	global_store_dword v136, v15, s[16:17]
	global_store_dword v136, v11, s[16:17] offset:64
	global_store_dword v136, v7, s[16:17] offset:512
	global_store_dword v136, v3, s[16:17] offset:576
	s_add_u32 s16, s16, 0x2000
	s_addc_u32 s17, s17, 0
	global_store_dword v136, v16, s[16:17]
	global_store_dword v136, v12, s[16:17] offset:64
	global_store_dword v136, v8, s[16:17] offset:512
	global_store_dword v136, v4, s[16:17] offset:576
	s_add_u32 s16, s16, 0x2000
	s_addc_u32 s17, s17, 0
	global_store_dword v136, v17, s[16:17]
	global_store_dword v136, v13, s[16:17] offset:64
	global_store_dword v136, v9, s[16:17] offset:512
	global_store_dword v136, v5, s[16:17] offset:576
	s_mov_b64 s[16:17], -1
	s_and_b64 vcc, exec, s[38:39]
	s_cbranch_vccnz .LBB0_346
	s_andn2_b64 vcc, exec, s[6:7]
	s_cbranch_vccnz .LBB0_345
	s_barrier
	s_branch .LBB0_345

; #define PG8_STAGE(bufoff, gbase, voff) do { _Pragma("unroll") for (int _i = 0; _i < 2; ++_i) \
;         __builtin_amdgcn_global_load_lds((const unsigned*)((const char*)(gbase) + (voff)[_i]), (PG8_LAS unsigned*)(lds + (bufoff) + ldsw + _i * 8192), 16, 0, 0); } while (0)
; #define PG8_LDA(dst, b, h) do { _Pragma("unroll") for (int m = 0; m < 4; ++m) _Pragma("unroll") for (int k = 0; k < 2; ++k) dst[m][k] = *(const PG8_LAS bf16x8*)(lds + PG8_SA(b, h) + aoff + m * 2048 + k * 1024); } while (0)
; #define PG8_LDB(dst, b, h) do { _Pragma("unroll") for (int n = 0; n < 2; ++n) _Pragma("unroll") for (int k = 0; k < 2; ++k) dst[n][k] = *(const PG8_LAS bf16x8*)(lds + PG8_SB(b, h) + boff + n * 2048 + k * 1024); } while (0)
; #define PG8_MMA(ai, bj, At, Bt) do { __builtin_amdgcn_s_setprio(1); _Pragma("unroll") for (int m = 0; m < 4; ++m) _Pragma("unroll") for (int n = 0; n < 2; ++n) _Pragma("unroll") for (int k = 0; k < 2; ++k) \
;         acc[ai][bj][m][n] = __builtin_amdgcn_mfma_f32_16x16x32_bf16(Bt[n][k], At[m][k], acc[ai][bj][m][n], 0, 0, 0); __builtin_amdgcn_s_setprio(0); } while (0)
; template <class Epi, class Sched, bool ALIGN_EPI = false, bool SP2 = false>
; __device__ __forceinline__ void gemm_phase(PG8_LAS unsigned char* lds, const Gemm g, const Sched& S, const Epi& E, int wave_s) {
;     ...
;         for (int t = 0; t < nt; t += 2) {
;             const bool last = (t == nt - 2);
;             const char* a1 = cA + (size_t)(t + 1) * kstep;
;             const char* a2 = last ? nA : cA + (size_t)(t + 2) * kstep; const char* b2 = last ? nB : cB + (size_t)(t + 2) * kstep;
;             const char* a3 = a2 + kstep; const char* b3 = b2 + kstep;
;             if (last && has_next) S.a_ready(nxt);
;             if constexpr (Epi::HAS_MID) { if (t == nt / 2) E.mid(acc, cur, wr, wc, fr, fq); }
;             if constexpr (SP2) {
;             PG8_LDB(B0, 0, 0); PG8_LDB(B1, 0, 1); PG8_SCHED; PG8_LDA(At, 0, 0); PG8_STAGE(PG8_SA(1, 1), a1 + hstepA, voffA);
;             PG8_WAIT_V(8); PG8_WAIT_L(0); PG8_BAR; PG8_MMA(0, 0, At, B0); PG8_MMA(0, 1, At, B1); PG8_BAR; PG8_SCHED;
;             PG8_LDA(At, 0, 1); PG8_STAGE(PG8_SB(0, 0), b2, voffB); PG8_STAGE(PG8_SB(0, 1), b2 + hstepB, voffB); PG8_STAGE(PG8_SA(0, 0), a2, voffA);
;             PG8_WAIT_V(8); PG8_WAIT_L(0); PG8_BAR; PG8_MMA(1, 0, At, B0); PG8_MMA(1, 1, At, B1); PG8_BAR; PG8_SCHED;
.LBB0_1674:
	s_add_u32 s20, s18, 0xfff80080
	s_addc_u32 s21, s19, -1
	s_add_i32 s34, 0, 0x10000
	s_cmp_eq_u32 s57, 28
	s_cselect_b32 s25, s13, s21
	s_cselect_b32 s24, s51, s20
	s_cselect_b32 s21, s11, s56
	s_cselect_b32 s20, s54, s55
	s_add_i32 s58, 0, 0x14000
	v_add_u32_e32 v94, s34, v159
	v_add_u32_e32 v156, s58, v159
	ds_read_b128 v[74:77], v94
	ds_read_b128 v[86:89], v94 offset:1024
	ds_read_b128 v[90:93], v94 offset:2048
	ds_read_b128 v[94:97], v94 offset:3072
	ds_read_b128 v[152:155], v156
	ds_read_b128 v[162:165], v156 offset:1024
	ds_read_b128 v[166:169], v156 offset:2048
	ds_read_b128 v[176:179], v156 offset:3072
	v_lshl_add_u64 v[156:157], s[18:19], 0, v[150:151]
	s_add_i32 m0, s42, 0xc000
	ds_read_b128 v[180:183], v161
	ds_read_b128 v[184:187], v161 offset:1024
	ds_read_b128 v[188:191], v161 offset:2048
	ds_read_b128 v[192:195], v161 offset:3072
	ds_read_b128 v[196:199], v161 offset:4096
	ds_read_b128 v[208:211], v161 offset:5120
	ds_read_b128 v[212:215], v161 offset:6144
	ds_read_b128 v[216:219], v161 offset:7168
	global_load_lds_dwordx4 v[156:157], off
	v_lshl_add_u64 v[156:157], s[18:19], 0, v[148:149]
	s_add_i32 m0, s42, 0xe000
	s_nop 0
	global_load_lds_dwordx4 v[156:157], off
	s_waitcnt vmcnt(8)
	s_waitcnt lgkmcnt(0)
	s_barrier
	s_setprio 1
	s_waitcnt lgkmcnt(0)
	v_mfma_f32_16x16x32_bf16 v[142:145], v[180:183], v[74:77], v[142:145]
	v_mfma_f32_16x16x32_bf16 v[138:141], v[180:183], v[90:93], v[138:141]
	v_mfma_f32_16x16x32_bf16 v[126:129], v[188:191], v[74:77], v[126:129]
	v_mfma_f32_16x16x32_bf16 v[122:125], v[188:191], v[90:93], v[122:125]
	v_mfma_f32_16x16x32_bf16 v[110:113], v[196:199], v[74:77], v[110:113]
	v_mfma_f32_16x16x32_bf16 v[106:109], v[196:199], v[90:93], v[106:109]
	v_mfma_f32_16x16x32_bf16 v[82:85], v[212:215], v[74:77], v[82:85]
	v_mfma_f32_16x16x32_bf16 v[78:81], v[212:215], v[90:93], v[78:81]
	v_mfma_f32_16x16x32_bf16 v[142:145], v[184:187], v[86:89], v[142:145]
	v_mfma_f32_16x16x32_bf16 v[138:141], v[184:187], v[94:97], v[138:141]
	v_mfma_f32_16x16x32_bf16 v[126:129], v[192:195], v[86:89], v[126:129]
	v_mfma_f32_16x16x32_bf16 v[122:125], v[192:195], v[94:97], v[122:125]
	v_mfma_f32_16x16x32_bf16 v[110:113], v[208:211], v[86:89], v[110:113]
	v_mfma_f32_16x16x32_bf16 v[106:109], v[208:211], v[94:97], v[106:109]
	v_mfma_f32_16x16x32_bf16 v[82:85], v[216:219], v[86:89], v[82:85]
	v_mfma_f32_16x16x32_bf16 v[78:81], v[216:219], v[94:97], v[78:81]
	s_setprio 0
	s_setprio 1
	v_mfma_f32_16x16x32_bf16 v[134:137], v[180:183], v[152:155], v[134:137]
	v_mfma_f32_16x16x32_bf16 v[130:133], v[180:183], v[166:169], v[130:133]
	v_mfma_f32_16x16x32_bf16 v[118:121], v[188:191], v[152:155], v[118:121]
	v_mfma_f32_16x16x32_bf16 v[114:117], v[188:191], v[166:169], v[114:117]
	v_mfma_f32_16x16x32_bf16 v[102:105], v[196:199], v[152:155], v[102:105]
	v_mfma_f32_16x16x32_bf16 v[98:101], v[196:199], v[166:169], v[98:101]
	v_mfma_f32_16x16x32_bf16 v[70:73], v[212:215], v[152:155], v[70:73]
	v_mfma_f32_16x16x32_bf16 v[66:69], v[212:215], v[166:169], v[66:69]
	v_mfma_f32_16x16x32_bf16 v[134:137], v[184:187], v[162:165], v[134:137]
	v_mfma_f32_16x16x32_bf16 v[130:133], v[184:187], v[176:179], v[130:133]
	v_mfma_f32_16x16x32_bf16 v[118:121], v[192:195], v[162:165], v[118:121]
	v_mfma_f32_16x16x32_bf16 v[114:117], v[192:195], v[176:179], v[114:117]
	v_mfma_f32_16x16x32_bf16 v[102:105], v[208:211], v[162:165], v[102:105]
	v_mfma_f32_16x16x32_bf16 v[98:101], v[208:211], v[176:179], v[98:101]
	v_mfma_f32_16x16x32_bf16 v[70:73], v[216:219], v[162:165], v[70:73]
	v_mfma_f32_16x16x32_bf16 v[66:69], v[216:219], v[176:179], v[66:69]
	s_setprio 0
	s_barrier
	s_add_i32 s34, s34, s37
	v_lshl_add_u64 v[156:157], s[20:21], 0, v[0:1]
	s_mov_b32 m0, s34
	ds_read_b128 v[180:183], v161 offset:16384
	ds_read_b128 v[184:187], v161 offset:17408
	ds_read_b128 v[188:191], v161 offset:18432
	ds_read_b128 v[192:195], v161 offset:19456
	ds_read_b128 v[196:199], v161 offset:20480
	ds_read_b128 v[208:211], v161 offset:21504
	ds_read_b128 v[212:215], v161 offset:22528
	ds_read_b128 v[216:219], v161 offset:23552
	global_load_lds_dwordx4 v[156:157], off
	s_add_i32 m0, s34, 0x2000
	s_add_u32 s34, s20, 0x80000
	v_lshl_add_u64 v[170:171], s[20:21], 0, v[146:147]
	s_addc_u32 s35, s21, 0
	s_add_i32 s58, s58, s37
	global_load_lds_dwordx4 v[170:171], off
	v_lshl_add_u64 v[200:201], s[34:35], 0, v[0:1]
	s_mov_b32 m0, s58
	v_lshl_add_u64 v[220:221], s[24:25], 0, v[146:147]
	global_load_lds_dwordx4 v[200:201], off
	v_lshl_add_u64 v[200:201], s[34:35], 0, v[146:147]
	s_add_i32 m0, s58, 0x2000
	s_nop 0
	global_load_lds_dwordx4 v[200:201], off
	v_lshl_add_u64 v[200:201], s[24:25], 0, v[0:1]
	s_mov_b32 m0, s42
	s_nop 0
	global_load_lds_dwordx4 v[200:201], off
	s_mov_b32 m0, s43
	s_nop 0
	global_load_lds_dwordx4 v[220:221], off
	s_waitcnt vmcnt(8)
	s_waitcnt lgkmcnt(0)
	s_barrier
; #define PG8_STAGE(bufoff, gbase, voff) do { _Pragma("unroll") for (int _i = 0; _i < 2; ++_i) \
;         __builtin_amdgcn_global_load_lds((const unsigned*)((const char*)(gbase) + (voff)[_i]), (PG8_LAS unsigned*)(lds + (bufoff) + ldsw + _i * 8192), 16, 0, 0); } while (0)
; #define PG8_LDA(dst, b, h) do { _Pragma("unroll") for (int m = 0; m < 4; ++m) _Pragma("unroll") for (int k = 0; k < 2; ++k) dst[m][k] = *(const PG8_LAS bf16x8*)(lds + PG8_SA(b, h) + aoff + m * 2048 + k * 1024); } while (0)
; #define PG8_LDB(dst, b, h) do { _Pragma("unroll") for (int n = 0; n < 2; ++n) _Pragma("unroll") for (int k = 0; k < 2; ++k) dst[n][k] = *(const PG8_LAS bf16x8*)(lds + PG8_SB(b, h) + boff + n * 2048 + k * 1024); } while (0)
; #define PG8_MMA(ai, bj, At, Bt) do { __builtin_amdgcn_s_setprio(1); _Pragma("unroll") for (int m = 0; m < 4; ++m) _Pragma("unroll") for (int n = 0; n < 2; ++n) _Pragma("unroll") for (int k = 0; k < 2; ++k) \
;         acc[ai][bj][m][n] = __builtin_amdgcn_mfma_f32_16x16x32_bf16(Bt[n][k], At[m][k], acc[ai][bj][m][n], 0, 0, 0); __builtin_amdgcn_s_setprio(0); } while (0)
; #define PG8_WAIT_V(n) asm volatile("s_waitcnt vmcnt(" #n ")" ::: "memory")
; #define PG8_WAIT_L(n) asm volatile("s_waitcnt lgkmcnt(" #n ")" ::: "memory")
; #define PG8_BAR __builtin_amdgcn_s_barrier()
; #define PG8_SCHED __builtin_amdgcn_sched_barrier(0)
; template <class Epi, class Sched, bool ALIGN_EPI = false, bool SP2 = false>
; __device__ __forceinline__ void gemm_phase(PG8_LAS unsigned char* lds, const Gemm g, const Sched& S, const Epi& E, int wave_s) {
;     ...
;             PG8_WAIT_V(8); PG8_WAIT_L(0); PG8_BAR; PG8_MMA(1, 0, At, B0); PG8_MMA(1, 1, At, B1); PG8_BAR; PG8_SCHED;
;             PG8_LDB(B0, 1, 0); PG8_LDB(B1, 1, 1); PG8_SCHED; PG8_LDA(At, 1, 0); PG8_STAGE(PG8_SA(0, 1), a2 + hstepA, voffA);
;             PG8_WAIT_V(8); PG8_WAIT_L(0); PG8_BAR; PG8_MMA(0, 0, At, B0); PG8_MMA(0, 1, At, B1); PG8_BAR; PG8_SCHED;
;             PG8_LDA(At, 1, 1); PG8_STAGE(PG8_SB(1, 0), b3, voffB); PG8_STAGE(PG8_SB(1, 1), b3 + hstepB, voffB); PG8_STAGE(PG8_SA(1, 0), a3, voffA);
	s_setprio 1
	s_waitcnt lgkmcnt(0)
	v_mfma_f32_16x16x32_bf16 v[62:65], v[180:183], v[74:77], v[62:65]
	v_mfma_f32_16x16x32_bf16 v[58:61], v[180:183], v[90:93], v[58:61]
	v_mfma_f32_16x16x32_bf16 v[46:49], v[188:191], v[74:77], v[46:49]
	v_mfma_f32_16x16x32_bf16 v[42:45], v[188:191], v[90:93], v[42:45]
	v_mfma_f32_16x16x32_bf16 v[30:33], v[196:199], v[74:77], v[30:33]
	v_mfma_f32_16x16x32_bf16 v[26:29], v[196:199], v[90:93], v[26:29]
	v_mfma_f32_16x16x32_bf16 v[14:17], v[212:215], v[74:77], v[14:17]
	v_mfma_f32_16x16x32_bf16 v[10:13], v[212:215], v[90:93], v[10:13]
	v_mfma_f32_16x16x32_bf16 v[62:65], v[184:187], v[86:89], v[62:65]
	v_mfma_f32_16x16x32_bf16 v[58:61], v[184:187], v[94:97], v[58:61]
	v_mfma_f32_16x16x32_bf16 v[46:49], v[192:195], v[86:89], v[46:49]
	v_mfma_f32_16x16x32_bf16 v[42:45], v[192:195], v[94:97], v[42:45]
	v_mfma_f32_16x16x32_bf16 v[30:33], v[208:211], v[86:89], v[30:33]
	v_mfma_f32_16x16x32_bf16 v[26:29], v[208:211], v[94:97], v[26:29]
	v_mfma_f32_16x16x32_bf16 v[14:17], v[216:219], v[86:89], v[14:17]
	v_mfma_f32_16x16x32_bf16 v[10:13], v[216:219], v[94:97], v[10:13]
	s_setprio 0
	s_setprio 1
	v_mfma_f32_16x16x32_bf16 v[54:57], v[180:183], v[152:155], v[54:57]
	v_mfma_f32_16x16x32_bf16 v[50:53], v[180:183], v[166:169], v[50:53]
	v_mfma_f32_16x16x32_bf16 v[38:41], v[188:191], v[152:155], v[38:41]
	v_mfma_f32_16x16x32_bf16 v[34:37], v[188:191], v[166:169], v[34:37]
	v_mfma_f32_16x16x32_bf16 v[22:25], v[196:199], v[152:155], v[22:25]
	v_mfma_f32_16x16x32_bf16 v[18:21], v[196:199], v[166:169], v[18:21]
	v_mfma_f32_16x16x32_bf16 v[6:9], v[212:215], v[152:155], v[6:9]
	v_mfma_f32_16x16x32_bf16 v[2:5], v[212:215], v[166:169], v[2:5]
	v_mfma_f32_16x16x32_bf16 v[54:57], v[184:187], v[162:165], v[54:57]
	v_mfma_f32_16x16x32_bf16 v[50:53], v[184:187], v[176:179], v[50:53]
	v_mfma_f32_16x16x32_bf16 v[38:41], v[192:195], v[162:165], v[38:41]
	v_mfma_f32_16x16x32_bf16 v[34:37], v[192:195], v[176:179], v[34:37]
	v_mfma_f32_16x16x32_bf16 v[22:25], v[208:211], v[162:165], v[22:25]
	v_mfma_f32_16x16x32_bf16 v[18:21], v[208:211], v[176:179], v[18:21]
	v_mfma_f32_16x16x32_bf16 v[6:9], v[216:219], v[162:165], v[6:9]
	v_mfma_f32_16x16x32_bf16 v[2:5], v[216:219], v[176:179], v[2:5]
	s_setprio 0
	s_barrier
	s_add_i32 s34, 0, 0x18000
	s_add_i32 s35, 0, 0x1c000
	v_add_u32_e32 v94, s34, v159
	v_add_u32_e32 v176, s35, v159
	ds_read_b128 v[74:77], v94
	ds_read_b128 v[86:89], v94 offset:1024
	ds_read_b128 v[90:93], v94 offset:2048
	ds_read_b128 v[94:97], v94 offset:3072
	ds_read_b128 v[152:155], v176
	ds_read_b128 v[162:165], v176 offset:1024
	ds_read_b128 v[166:169], v176 offset:2048
	ds_read_b128 v[176:179], v176 offset:3072
	s_add_u32 s24, s24, 0x80000
	s_addc_u32 s25, s25, 0
	s_mov_b32 m0, s44
	v_lshl_add_u64 v[222:223], s[24:25], 0, v[0:1]
	ds_read_b128 v[180:183], v161 offset:32768
	ds_read_b128 v[184:187], v161 offset:33792
	ds_read_b128 v[188:191], v161 offset:34816
	ds_read_b128 v[192:195], v161 offset:35840
	ds_read_b128 v[196:199], v161 offset:36864
	ds_read_b128 v[208:211], v161 offset:37888
	ds_read_b128 v[212:215], v161 offset:38912
	ds_read_b128 v[216:219], v161 offset:39936
	global_load_lds_dwordx4 v[222:223], off
	v_lshl_add_u64 v[222:223], s[24:25], 0, v[146:147]
	s_mov_b32 m0, s45
	s_nop 0
	global_load_lds_dwordx4 v[222:223], off
	s_waitcnt vmcnt(8)
	s_waitcnt lgkmcnt(0)
	s_barrier
	s_setprio 1
	s_waitcnt lgkmcnt(0)
	v_mfma_f32_16x16x32_bf16 v[142:145], v[180:183], v[74:77], v[142:145]
	v_mfma_f32_16x16x32_bf16 v[138:141], v[180:183], v[90:93], v[138:141]
	v_mfma_f32_16x16x32_bf16 v[126:129], v[188:191], v[74:77], v[126:129]
	v_mfma_f32_16x16x32_bf16 v[122:125], v[188:191], v[90:93], v[122:125]
	v_mfma_f32_16x16x32_bf16 v[110:113], v[196:199], v[74:77], v[110:113]
	v_mfma_f32_16x16x32_bf16 v[106:109], v[196:199], v[90:93], v[106:109]
	v_mfma_f32_16x16x32_bf16 v[82:85], v[212:215], v[74:77], v[82:85]
	v_mfma_f32_16x16x32_bf16 v[78:81], v[212:215], v[90:93], v[78:81]
	v_mfma_f32_16x16x32_bf16 v[142:145], v[184:187], v[86:89], v[142:145]
	v_mfma_f32_16x16x32_bf16 v[138:141], v[184:187], v[94:97], v[138:141]
	v_mfma_f32_16x16x32_bf16 v[126:129], v[192:195], v[86:89], v[126:129]
	v_mfma_f32_16x16x32_bf16 v[122:125], v[192:195], v[94:97], v[122:125]
	v_mfma_f32_16x16x32_bf16 v[110:113], v[208:211], v[86:89], v[110:113]
	v_mfma_f32_16x16x32_bf16 v[106:109], v[208:211], v[94:97], v[106:109]
	v_mfma_f32_16x16x32_bf16 v[82:85], v[216:219], v[86:89], v[82:85]
	v_mfma_f32_16x16x32_bf16 v[78:81], v[216:219], v[94:97], v[78:81]
	s_setprio 0
	s_setprio 1
	v_mfma_f32_16x16x32_bf16 v[134:137], v[180:183], v[152:155], v[134:137]
	v_mfma_f32_16x16x32_bf16 v[130:133], v[180:183], v[166:169], v[130:133]
	v_mfma_f32_16x16x32_bf16 v[118:121], v[188:191], v[152:155], v[118:121]
	v_mfma_f32_16x16x32_bf16 v[114:117], v[188:191], v[166:169], v[114:117]
	v_mfma_f32_16x16x32_bf16 v[102:105], v[196:199], v[152:155], v[102:105]
	v_mfma_f32_16x16x32_bf16 v[98:101], v[196:199], v[166:169], v[98:101]
	v_mfma_f32_16x16x32_bf16 v[70:73], v[212:215], v[152:155], v[70:73]
	v_mfma_f32_16x16x32_bf16 v[66:69], v[212:215], v[166:169], v[66:69]
	v_mfma_f32_16x16x32_bf16 v[134:137], v[184:187], v[162:165], v[134:137]
	v_mfma_f32_16x16x32_bf16 v[130:133], v[184:187], v[176:179], v[130:133]
	v_mfma_f32_16x16x32_bf16 v[118:121], v[192:195], v[162:165], v[118:121]
	v_mfma_f32_16x16x32_bf16 v[114:117], v[192:195], v[176:179], v[114:117]
	v_mfma_f32_16x16x32_bf16 v[102:105], v[208:211], v[162:165], v[102:105]
	v_mfma_f32_16x16x32_bf16 v[98:101], v[208:211], v[176:179], v[98:101]
	v_mfma_f32_16x16x32_bf16 v[70:73], v[216:219], v[162:165], v[70:73]
	v_mfma_f32_16x16x32_bf16 v[66:69], v[216:219], v[176:179], v[66:69]
	s_setprio 0
	s_barrier
; #define PG8_STAGE(bufoff, gbase, voff) do { _Pragma("unroll") for (int _i = 0; _i < 2; ++_i) \
;         __builtin_amdgcn_global_load_lds((const unsigned*)((const char*)(gbase) + (voff)[_i]), (PG8_LAS unsigned*)(lds + (bufoff) + ldsw + _i * 8192), 16, 0, 0); } while (0)
; #define PG8_LDA(dst, b, h) do { _Pragma("unroll") for (int m = 0; m < 4; ++m) _Pragma("unroll") for (int k = 0; k < 2; ++k) dst[m][k] = *(const PG8_LAS bf16x8*)(lds + PG8_SA(b, h) + aoff + m * 2048 + k * 1024); } while (0)
; #define PG8_WAIT_V(n) asm volatile("s_waitcnt vmcnt(" #n ")" ::: "memory")
; #define PG8_WAIT_L(n) asm volatile("s_waitcnt lgkmcnt(" #n ")" ::: "memory")
; #define PG8_BAR __builtin_amdgcn_s_barrier()
; #define PG8_SCHED __builtin_amdgcn_sched_barrier(0)
; template <class Epi, class Sched, bool ALIGN_EPI = false, bool SP2 = false>
; __device__ __forceinline__ void gemm_phase(PG8_LAS unsigned char* lds, const Gemm g, const Sched& S, const Epi& E, int wave_s) {
;     ...
;             PG8_LDA(At, 1, 1); PG8_STAGE(PG8_SB(1, 0), b3, voffB); PG8_STAGE(PG8_SB(1, 1), b3 + hstepB, voffB); PG8_STAGE(PG8_SA(1, 0), a3, voffA);
;             PG8_WAIT_V(8); PG8_WAIT_L(0); PG8_BAR; PG8_MMA(1, 0, At, B0); PG8_MMA(1, 1, At, B1); PG8_BAR; PG8_SCHED;
;     __device__ __forceinline__ void operator()(const pg8::f32x4 (&acc)[2][2][4][2], const pg8::Unit& u, int wr, int wc, int fr, int fq) const {
;         const int b = u.pm >> 4;
;         const int row0 = u.pm * 256 + wr * 64 + fr, col0 = u.pn * 256 + wc * 32 + 4 * fq;
;         pg8::f32x4 gv[2][2];
; #pragma unroll
;         for (int bj = 0; bj < 2; ++bj)
; #pragma unroll
;             for (int n = 0; n < 2; ++n) gv[bj][n] = *(const pg8::f32x4*)(gate + (size_t)b * NMOD + col0 + bj * 128 + n * 16) * coef;
; #pragma unroll
;         for (int ai = 0; ai < 2; ++ai)
; #pragma unroll
;             for (int m = 0; m < 4; ++m) { const size_t off = (size_t)(row0 + ai * 128 + m * 16) * D + col0;
; #pragma unroll
;                 for (int bj = 0; bj < 2; ++bj)
; #pragma unroll
;                     for (int n = 0; n < 2; ++n) { const pg8::f32x4 xv = *(const pg8::f32x4*)(xin + off + bj * 128 + n * 16);
;                         *(pg8::f32x4*)(xout + off + bj * 128 + n * 16) = xv + gv[bj][n] * acc[ai][bj][m][n]; }
;                 if (m & 1) asm volatile("" ::: "memory"); }
	s_add_i32 s24, s34, s37
	v_lshl_add_u64 v[156:157], v[156:157], 0, s[30:31]
	s_mov_b32 m0, s24
	ds_read_b128 v[180:183], v161 offset:49152
	ds_read_b128 v[184:187], v161 offset:50176
	ds_read_b128 v[188:191], v161 offset:51200
	ds_read_b128 v[192:195], v161 offset:52224
	ds_read_b128 v[196:199], v161 offset:53248
	ds_read_b128 v[208:211], v161 offset:54272
	ds_read_b128 v[212:215], v161 offset:55296
	ds_read_b128 v[216:219], v161 offset:56320
	global_load_lds_dwordx4 v[156:157], off
	s_add_i32 m0, s24, 0x2000
	s_add_u32 s20, s20, 0x80080
	v_lshl_add_u64 v[156:157], v[170:171], 0, s[30:31]
	s_addc_u32 s21, s21, 0
	s_add_i32 s24, s35, s37
	global_load_lds_dwordx4 v[156:157], off
	v_lshl_add_u64 v[156:157], s[20:21], 0, v[0:1]
	s_mov_b32 m0, s24
	s_nop 0
	global_load_lds_dwordx4 v[156:157], off
	v_lshl_add_u64 v[156:157], s[20:21], 0, v[146:147]
	s_add_i32 m0, s24, 0x2000
	s_nop 0
	global_load_lds_dwordx4 v[156:157], off
	v_lshl_add_u64 v[156:157], v[200:201], 0, s[30:31]
	s_mov_b32 m0, s48
	s_nop 0
	global_load_lds_dwordx4 v[156:157], off
	v_lshl_add_u64 v[156:157], v[220:221], 0, s[30:31]
	s_mov_b32 m0, s49
	s_nop 0
	global_load_lds_dwordx4 v[156:157], off
	s_waitcnt vmcnt(8)
	s_waitcnt lgkmcnt(0)
	s_barrier
	s_setprio 1
	s_waitcnt lgkmcnt(0)
	v_mfma_f32_16x16x32_bf16 v[62:65], v[180:183], v[74:77], v[62:65]
	v_mfma_f32_16x16x32_bf16 v[58:61], v[180:183], v[90:93], v[58:61]
	v_mfma_f32_16x16x32_bf16 v[46:49], v[188:191], v[74:77], v[46:49]
	v_mfma_f32_16x16x32_bf16 v[42:45], v[188:191], v[90:93], v[42:45]
	v_mfma_f32_16x16x32_bf16 v[30:33], v[196:199], v[74:77], v[30:33]
	v_mfma_f32_16x16x32_bf16 v[26:29], v[196:199], v[90:93], v[26:29]
	v_mfma_f32_16x16x32_bf16 v[14:17], v[212:215], v[74:77], v[14:17]
	v_mfma_f32_16x16x32_bf16 v[10:13], v[212:215], v[90:93], v[10:13]
	v_mfma_f32_16x16x32_bf16 v[62:65], v[184:187], v[86:89], v[62:65]
	v_mfma_f32_16x16x32_bf16 v[58:61], v[184:187], v[94:97], v[58:61]
	v_mfma_f32_16x16x32_bf16 v[46:49], v[192:195], v[86:89], v[46:49]
	v_mfma_f32_16x16x32_bf16 v[42:45], v[192:195], v[94:97], v[42:45]
	v_mfma_f32_16x16x32_bf16 v[30:33], v[208:211], v[86:89], v[30:33]
	v_mfma_f32_16x16x32_bf16 v[26:29], v[208:211], v[94:97], v[26:29]
	v_mfma_f32_16x16x32_bf16 v[14:17], v[216:219], v[86:89], v[14:17]
	v_mfma_f32_16x16x32_bf16 v[10:13], v[216:219], v[94:97], v[10:13]
	s_setprio 0
	s_setprio 1
	v_mfma_f32_16x16x32_bf16 v[54:57], v[180:183], v[152:155], v[54:57]
	v_mfma_f32_16x16x32_bf16 v[50:53], v[180:183], v[166:169], v[50:53]
	v_mfma_f32_16x16x32_bf16 v[38:41], v[188:191], v[152:155], v[38:41]
	v_mfma_f32_16x16x32_bf16 v[34:37], v[188:191], v[166:169], v[34:37]
	v_mfma_f32_16x16x32_bf16 v[22:25], v[196:199], v[152:155], v[22:25]
	v_mfma_f32_16x16x32_bf16 v[18:21], v[196:199], v[166:169], v[18:21]
	v_mfma_f32_16x16x32_bf16 v[6:9], v[212:215], v[152:155], v[6:9]
	v_mfma_f32_16x16x32_bf16 v[2:5], v[212:215], v[166:169], v[2:5]
	v_mfma_f32_16x16x32_bf16 v[54:57], v[184:187], v[162:165], v[54:57]
	v_mfma_f32_16x16x32_bf16 v[50:53], v[184:187], v[176:179], v[50:53]
	v_mfma_f32_16x16x32_bf16 v[38:41], v[192:195], v[162:165], v[38:41]
	v_mfma_f32_16x16x32_bf16 v[34:37], v[192:195], v[176:179], v[34:37]
	v_mfma_f32_16x16x32_bf16 v[22:25], v[208:211], v[162:165], v[22:25]
	v_mfma_f32_16x16x32_bf16 v[18:21], v[208:211], v[176:179], v[18:21]
	v_mfma_f32_16x16x32_bf16 v[6:9], v[216:219], v[162:165], v[6:9]
	v_mfma_f32_16x16x32_bf16 v[2:5], v[216:219], v[176:179], v[2:5]
	s_setprio 0
	s_barrier
	s_add_i32 s57, s57, 2
	s_add_u32 s55, s55, 0x100
	s_addc_u32 s56, s56, 0
	s_add_u32 s18, s18, 0x100
	s_addc_u32 s19, s19, 0
	s_cmp_gt_u32 s57, 29
	s_cbranch_scc0 .LBB0_1674
	s_and_b64 vcc, exec, s[8:9]
	s_cbranch_vccz .LBB0_1677
	s_barrier
.LBB0_1677:
	v_and_b32_e32 v74, 0x40, v158
	v_and_b32_e32 v75, 12, v160
	v_or_b32_e32 v74, v74, v75
	v_and_b32_e32 v75, 0x60, v160
	v_and_or_b32 v75, v158, 15, v75
	v_lshlrev_b32_e32 v75, 2, v75
	v_lshl_add_u32 v74, v74, 13, v75
	s_ashr_i32 vcc_hi, s26, 4
	s_mul_i32 vcc_hi, vcc_hi, 0x12000
	s_lshl_b32 vcc_lo, s27, 10
	s_add_u32 vcc_hi, vcc_hi, vcc_lo
	s_add_u32 s18, s46, vcc_hi
	s_addc_u32 s19, s47, 0
	global_load_dword v76, v75, s[18:19]
	global_load_dword v77, v75, s[18:19] offset:64
	global_load_dword v86, v75, s[18:19] offset:512
	global_load_dword v87, v75, s[18:19] offset:576
	s_lshl_b32 vcc_hi, s26, 21
	s_add_u32 vcc_lo, vcc_lo, vcc_hi
	s_add_u32 s100, s6, vcc_lo
	s_addc_u32 s101, s7, 0
	s_add_u32 s18, s6, vcc_lo
	s_addc_u32 s19, s7, 0
	global_load_dword v88, v74, s[100:101]
	global_load_dword v89, v74, s[100:101] offset:64
	global_load_dword v90, v74, s[100:101] offset:512
	global_load_dword v91, v74, s[100:101] offset:576
	s_add_u32 s100, s100, 0x2000
	s_addc_u32 s101, s101, 0
	global_load_dword v92, v74, s[100:101]
	global_load_dword v93, v74, s[100:101] offset:64
	global_load_dword v94, v74, s[100:101] offset:512
	global_load_dword v95, v74, s[100:101] offset:576
	s_add_u32 s100, s100, 0x2000
	s_addc_u32 s101, s101, 0
	global_load_dword v96, v74, s[100:101]
	global_load_dword v97, v74, s[100:101] offset:64
	global_load_dword v152, v74, s[100:101] offset:512
	global_load_dword v153, v74, s[100:101] offset:576
	s_add_u32 s100, s100, 0x2000
	s_addc_u32 s101, s101, 0
	global_load_dword v154, v74, s[100:101]
	global_load_dword v155, v74, s[100:101] offset:64
	global_load_dword v162, v74, s[100:101] offset:512
	global_load_dword v163, v74, s[100:101] offset:576
	s_add_u32 s100, s100, 0x1a000
	s_addc_u32 s101, s101, 0
	global_load_dword v164, v74, s[100:101]
	global_load_dword v165, v74, s[100:101] offset:64
	global_load_dword v166, v74, s[100:101] offset:512
	global_load_dword v167, v74, s[100:101] offset:576
	s_add_u32 s100, s100, 0x2000
	s_addc_u32 s101, s101, 0
	global_load_dword v168, v74, s[100:101]
	global_load_dword v169, v74, s[100:101] offset:64
	global_load_dword v176, v74, s[100:101] offset:512
	global_load_dword v177, v74, s[100:101] offset:576
	s_add_u32 s100, s100, 0x2000
	s_addc_u32 s101, s101, 0
	global_load_dword v178, v74, s[100:101]
	global_load_dword v179, v74, s[100:101] offset:64
	global_load_dword v180, v74, s[100:101] offset:512
	global_load_dword v181, v74, s[100:101] offset:576
	s_add_u32 s100, s100, 0x2000
	s_addc_u32 s101, s101, 0
	global_load_dword v182, v74, s[100:101]
	global_load_dword v183, v74, s[100:101] offset:64
	global_load_dword v184, v74, s[100:101] offset:512
	global_load_dword v185, v74, s[100:101] offset:576
	s_add_u32 s100, s100, 0x1a000
	s_addc_u32 s101, s101, 0
	s_waitcnt vmcnt(16)
;     __device__ __forceinline__ void operator()(const pg8::f32x4 (&acc)[2][2][4][2], const pg8::Unit& u, int wr, int wc, int fr, int fq) const {
;     ...
;         for (int ai = 0; ai < 2; ++ai)
; #pragma unroll
;             for (int m = 0; m < 4; ++m) { const size_t off = (size_t)(row0 + ai * 128 + m * 16) * D + col0;
; #pragma unroll
;                 for (int bj = 0; bj < 2; ++bj)
; #pragma unroll
;                     for (int n = 0; n < 2; ++n) { const pg8::f32x4 xv = *(const pg8::f32x4*)(xin + off + bj * 128 + n * 16);
;                         *(pg8::f32x4*)(xout + off + bj * 128 + n * 16) = xv + gv[bj][n] * acc[ai][bj][m][n]; }
;                 if (m & 1) asm volatile("" ::: "memory"); }
	v_fma_f32 v142, v142, v76, v88
	v_fma_f32 v138, v138, v77, v89
	v_fma_f32 v134, v134, v86, v90
	v_fma_f32 v130, v130, v87, v91
	v_fma_f32 v143, v143, v76, v92
	v_fma_f32 v139, v139, v77, v93
	v_fma_f32 v135, v135, v86, v94
	v_fma_f32 v131, v131, v87, v95
	v_fma_f32 v144, v144, v76, v96
	v_fma_f32 v140, v140, v77, v97
	v_fma_f32 v136, v136, v86, v152
	v_fma_f32 v132, v132, v87, v153
	v_fma_f32 v145, v145, v76, v154
	v_fma_f32 v141, v141, v77, v155
	v_fma_f32 v137, v137, v86, v162
	v_fma_f32 v133, v133, v87, v163
	global_store_dword v74, v142, s[18:19]
	global_store_dword v74, v138, s[18:19] offset:64
	global_store_dword v74, v134, s[18:19] offset:512
	global_store_dword v74, v130, s[18:19] offset:576
	s_add_u32 s18, s18, 0x2000
	s_addc_u32 s19, s19, 0
	global_store_dword v74, v143, s[18:19]
	global_store_dword v74, v139, s[18:19] offset:64
	global_store_dword v74, v135, s[18:19] offset:512
	global_store_dword v74, v131, s[18:19] offset:576
	s_add_u32 s18, s18, 0x2000
	s_addc_u32 s19, s19, 0
	global_store_dword v74, v144, s[18:19]
	global_store_dword v74, v140, s[18:19] offset:64
	global_store_dword v74, v136, s[18:19] offset:512
	global_store_dword v74, v132, s[18:19] offset:576
	s_add_u32 s18, s18, 0x2000
	s_addc_u32 s19, s19, 0
	global_store_dword v74, v145, s[18:19]
	global_store_dword v74, v141, s[18:19] offset:64
	global_store_dword v74, v137, s[18:19] offset:512
	global_store_dword v74, v133, s[18:19] offset:576
	s_add_u32 s18, s18, 0x1a000
	s_addc_u32 s19, s19, 0
	global_load_dword v88, v74, s[100:101]
	global_load_dword v89, v74, s[100:101] offset:64
	global_load_dword v90, v74, s[100:101] offset:512
	global_load_dword v91, v74, s[100:101] offset:576
	s_add_u32 s100, s100, 0x2000
	s_addc_u32 s101, s101, 0
	global_load_dword v92, v74, s[100:101]
	global_load_dword v93, v74, s[100:101] offset:64
	global_load_dword v94, v74, s[100:101] offset:512
	global_load_dword v95, v74, s[100:101] offset:576
	s_add_u32 s100, s100, 0x2000
	s_addc_u32 s101, s101, 0
	global_load_dword v96, v74, s[100:101]
	global_load_dword v97, v74, s[100:101] offset:64
	global_load_dword v152, v74, s[100:101] offset:512
	global_load_dword v153, v74, s[100:101] offset:576
	s_add_u32 s100, s100, 0x2000
	s_addc_u32 s101, s101, 0
	global_load_dword v154, v74, s[100:101]
	global_load_dword v155, v74, s[100:101] offset:64
	global_load_dword v162, v74, s[100:101] offset:512
	global_load_dword v163, v74, s[100:101] offset:576
	s_add_u32 s100, s100, 0x1a000
	s_addc_u32 s101, s101, 0
	s_waitcnt vmcnt(32)
	v_fma_f32 v126, v126, v76, v164
	v_fma_f32 v122, v122, v77, v165
	v_fma_f32 v118, v118, v86, v166
	v_fma_f32 v114, v114, v87, v167
	v_fma_f32 v127, v127, v76, v168
	v_fma_f32 v123, v123, v77, v169
	v_fma_f32 v119, v119, v86, v176
	v_fma_f32 v115, v115, v87, v177
	v_fma_f32 v128, v128, v76, v178
	v_fma_f32 v124, v124, v77, v179
	v_fma_f32 v120, v120, v86, v180
	v_fma_f32 v116, v116, v87, v181
	v_fma_f32 v129, v129, v76, v182
	v_fma_f32 v125, v125, v77, v183
	v_fma_f32 v121, v121, v86, v184
	v_fma_f32 v117, v117, v87, v185
	global_store_dword v74, v126, s[18:19]
	global_store_dword v74, v122, s[18:19] offset:64
	global_store_dword v74, v118, s[18:19] offset:512
	global_store_dword v74, v114, s[18:19] offset:576
	s_add_u32 s18, s18, 0x2000
	s_addc_u32 s19, s19, 0
	global_store_dword v74, v127, s[18:19]
	global_store_dword v74, v123, s[18:19] offset:64
	global_store_dword v74, v119, s[18:19] offset:512
	global_store_dword v74, v115, s[18:19] offset:576
	s_add_u32 s18, s18, 0x2000
	s_addc_u32 s19, s19, 0
	global_store_dword v74, v128, s[18:19]
	global_store_dword v74, v124, s[18:19] offset:64
	global_store_dword v74, v120, s[18:19] offset:512
	global_store_dword v74, v116, s[18:19] offset:576
	s_add_u32 s18, s18, 0x2000
	s_addc_u32 s19, s19, 0
	global_store_dword v74, v129, s[18:19]
	global_store_dword v74, v125, s[18:19] offset:64
	global_store_dword v74, v121, s[18:19] offset:512
	global_store_dword v74, v117, s[18:19] offset:576
	s_add_u32 s18, s18, 0x1a000
	s_addc_u32 s19, s19, 0
	global_load_dword v164, v74, s[100:101]
	global_load_dword v165, v74, s[100:101] offset:64
	global_load_dword v166, v74, s[100:101] offset:512
	global_load_dword v167, v74, s[100:101] offset:576
	s_add_u32 s100, s100, 0x2000
	s_addc_u32 s101, s101, 0
	global_load_dword v168, v74, s[100:101]
	global_load_dword v169, v74, s[100:101] offset:64
	global_load_dword v176, v74, s[100:101] offset:512
	global_load_dword v177, v74, s[100:101] offset:576
	s_add_u32 s100, s100, 0x2000
	s_addc_u32 s101, s101, 0
	global_load_dword v178, v74, s[100:101]
	global_load_dword v179, v74, s[100:101] offset:64
	global_load_dword v180, v74, s[100:101] offset:512
	global_load_dword v181, v74, s[100:101] offset:576
	s_add_u32 s100, s100, 0x2000
	s_addc_u32 s101, s101, 0
	global_load_dword v182, v74, s[100:101]
	global_load_dword v183, v74, s[100:101] offset:64
	global_load_dword v184, v74, s[100:101] offset:512
	global_load_dword v185, v74, s[100:101] offset:576
	s_add_u32 s100, s100, 0x9a000
	s_addc_u32 s101, s101, 0
	s_waitcnt vmcnt(32)
;     __device__ __forceinline__ void operator()(const pg8::f32x4 (&acc)[2][2][4][2], const pg8::Unit& u, int wr, int wc, int fr, int fq) const {
;     ...
;         for (int ai = 0; ai < 2; ++ai)
; #pragma unroll
;             for (int m = 0; m < 4; ++m) { const size_t off = (size_t)(row0 + ai * 128 + m * 16) * D + col0;
; #pragma unroll
;                 for (int bj = 0; bj < 2; ++bj)
; #pragma unroll
;                     for (int n = 0; n < 2; ++n) { const pg8::f32x4 xv = *(const pg8::f32x4*)(xin + off + bj * 128 + n * 16);
;                         *(pg8::f32x4*)(xout + off + bj * 128 + n * 16) = xv + gv[bj][n] * acc[ai][bj][m][n]; }
;                 if (m & 1) asm volatile("" ::: "memory"); }
	v_fma_f32 v110, v110, v76, v88
	v_fma_f32 v106, v106, v77, v89
	v_fma_f32 v102, v102, v86, v90
	v_fma_f32 v98, v98, v87, v91
	v_fma_f32 v111, v111, v76, v92
	v_fma_f32 v107, v107, v77, v93
	v_fma_f32 v103, v103, v86, v94
	v_fma_f32 v99, v99, v87, v95
	v_fma_f32 v112, v112, v76, v96
	v_fma_f32 v108, v108, v77, v97
	v_fma_f32 v104, v104, v86, v152
	v_fma_f32 v100, v100, v87, v153
	v_fma_f32 v113, v113, v76, v154
	v_fma_f32 v109, v109, v77, v155
	v_fma_f32 v105, v105, v86, v162
	v_fma_f32 v101, v101, v87, v163
	global_store_dword v74, v110, s[18:19]
	global_store_dword v74, v106, s[18:19] offset:64
	global_store_dword v74, v102, s[18:19] offset:512
	global_store_dword v74, v98, s[18:19] offset:576
	s_add_u32 s18, s18, 0x2000
	s_addc_u32 s19, s19, 0
	global_store_dword v74, v111, s[18:19]
	global_store_dword v74, v107, s[18:19] offset:64
	global_store_dword v74, v103, s[18:19] offset:512
	global_store_dword v74, v99, s[18:19] offset:576
	s_add_u32 s18, s18, 0x2000
	s_addc_u32 s19, s19, 0
	global_store_dword v74, v112, s[18:19]
	global_store_dword v74, v108, s[18:19] offset:64
	global_store_dword v74, v104, s[18:19] offset:512
	global_store_dword v74, v100, s[18:19] offset:576
	s_add_u32 s18, s18, 0x2000
	s_addc_u32 s19, s19, 0
	global_store_dword v74, v113, s[18:19]
	global_store_dword v74, v109, s[18:19] offset:64
	global_store_dword v74, v105, s[18:19] offset:512
	global_store_dword v74, v101, s[18:19] offset:576
	s_add_u32 s18, s18, 0x1a000
	s_addc_u32 s19, s19, 0
	global_load_dword v88, v74, s[100:101]
	global_load_dword v89, v74, s[100:101] offset:64
	global_load_dword v90, v74, s[100:101] offset:512
	global_load_dword v91, v74, s[100:101] offset:576
	s_add_u32 s100, s100, 0x2000
	s_addc_u32 s101, s101, 0
	global_load_dword v92, v74, s[100:101]
	global_load_dword v93, v74, s[100:101] offset:64
	global_load_dword v94, v74, s[100:101] offset:512
	global_load_dword v95, v74, s[100:101] offset:576
	s_add_u32 s100, s100, 0x2000
	s_addc_u32 s101, s101, 0
	global_load_dword v96, v74, s[100:101]
	global_load_dword v97, v74, s[100:101] offset:64
	global_load_dword v152, v74, s[100:101] offset:512
	global_load_dword v153, v74, s[100:101] offset:576
	s_add_u32 s100, s100, 0x2000
	s_addc_u32 s101, s101, 0
	global_load_dword v154, v74, s[100:101]
	global_load_dword v155, v74, s[100:101] offset:64
	global_load_dword v162, v74, s[100:101] offset:512
	global_load_dword v163, v74, s[100:101] offset:576
	s_add_u32 s100, s100, 0x1a000
	s_addc_u32 s101, s101, 0
	s_waitcnt vmcnt(32)
	v_fma_f32 v82, v82, v76, v164
	v_fma_f32 v78, v78, v77, v165
	v_fma_f32 v70, v70, v86, v166
	v_fma_f32 v66, v66, v87, v167
	v_fma_f32 v83, v83, v76, v168
	v_fma_f32 v79, v79, v77, v169
	v_fma_f32 v71, v71, v86, v176
	v_fma_f32 v67, v67, v87, v177
	v_fma_f32 v84, v84, v76, v178
	v_fma_f32 v80, v80, v77, v179
	v_fma_f32 v72, v72, v86, v180
	v_fma_f32 v68, v68, v87, v181
	v_fma_f32 v85, v85, v76, v182
	v_fma_f32 v81, v81, v77, v183
	v_fma_f32 v73, v73, v86, v184
	v_fma_f32 v69, v69, v87, v185
	global_store_dword v74, v82, s[18:19]
	global_store_dword v74, v78, s[18:19] offset:64
	global_store_dword v74, v70, s[18:19] offset:512
	global_store_dword v74, v66, s[18:19] offset:576
	s_add_u32 s18, s18, 0x2000
	s_addc_u32 s19, s19, 0
	global_store_dword v74, v83, s[18:19]
	global_store_dword v74, v79, s[18:19] offset:64
	global_store_dword v74, v71, s[18:19] offset:512
	global_store_dword v74, v67, s[18:19] offset:576
	s_add_u32 s18, s18, 0x2000
	s_addc_u32 s19, s19, 0
	global_store_dword v74, v84, s[18:19]
	global_store_dword v74, v80, s[18:19] offset:64
	global_store_dword v74, v72, s[18:19] offset:512
	global_store_dword v74, v68, s[18:19] offset:576
	s_add_u32 s18, s18, 0x2000
	s_addc_u32 s19, s19, 0
	global_store_dword v74, v85, s[18:19]
	global_store_dword v74, v81, s[18:19] offset:64
	global_store_dword v74, v73, s[18:19] offset:512
	global_store_dword v74, v69, s[18:19] offset:576
	s_add_u32 s18, s18, 0x9a000
	s_addc_u32 s19, s19, 0
	global_load_dword v164, v74, s[100:101]
	global_load_dword v165, v74, s[100:101] offset:64
	global_load_dword v166, v74, s[100:101] offset:512
	global_load_dword v167, v74, s[100:101] offset:576
	s_add_u32 s100, s100, 0x2000
	s_addc_u32 s101, s101, 0
	global_load_dword v168, v74, s[100:101]
	global_load_dword v169, v74, s[100:101] offset:64
	global_load_dword v176, v74, s[100:101] offset:512
	global_load_dword v177, v74, s[100:101] offset:576
	s_add_u32 s100, s100, 0x2000
	s_addc_u32 s101, s101, 0
	global_load_dword v178, v74, s[100:101]
	global_load_dword v179, v74, s[100:101] offset:64
	global_load_dword v180, v74, s[100:101] offset:512
	global_load_dword v181, v74, s[100:101] offset:576
	s_add_u32 s100, s100, 0x2000
	s_addc_u32 s101, s101, 0
	global_load_dword v182, v74, s[100:101]
	global_load_dword v183, v74, s[100:101] offset:64
	global_load_dword v184, v74, s[100:101] offset:512
	global_load_dword v185, v74, s[100:101] offset:576
	s_add_u32 s100, s100, 0x1a000
	s_addc_u32 s101, s101, 0
	s_waitcnt vmcnt(32)
;     __device__ __forceinline__ void operator()(const pg8::f32x4 (&acc)[2][2][4][2], const pg8::Unit& u, int wr, int wc, int fr, int fq) const {
;     ...
;         for (int ai = 0; ai < 2; ++ai)
; #pragma unroll
;             for (int m = 0; m < 4; ++m) { const size_t off = (size_t)(row0 + ai * 128 + m * 16) * D + col0;
; #pragma unroll
;                 for (int bj = 0; bj < 2; ++bj)
; #pragma unroll
;                     for (int n = 0; n < 2; ++n) { const pg8::f32x4 xv = *(const pg8::f32x4*)(xin + off + bj * 128 + n * 16);
;                         *(pg8::f32x4*)(xout + off + bj * 128 + n * 16) = xv + gv[bj][n] * acc[ai][bj][m][n]; }
;                 if (m & 1) asm volatile("" ::: "memory"); }
	v_fma_f32 v62, v62, v76, v88
	v_fma_f32 v58, v58, v77, v89
	v_fma_f32 v54, v54, v86, v90
	v_fma_f32 v50, v50, v87, v91
	v_fma_f32 v63, v63, v76, v92
	v_fma_f32 v59, v59, v77, v93
	v_fma_f32 v55, v55, v86, v94
	v_fma_f32 v51, v51, v87, v95
	v_fma_f32 v64, v64, v76, v96
	v_fma_f32 v60, v60, v77, v97
	v_fma_f32 v56, v56, v86, v152
	v_fma_f32 v52, v52, v87, v153
	v_fma_f32 v65, v65, v76, v154
	v_fma_f32 v61, v61, v77, v155
	v_fma_f32 v57, v57, v86, v162
	v_fma_f32 v53, v53, v87, v163
	global_store_dword v74, v62, s[18:19]
	global_store_dword v74, v58, s[18:19] offset:64
	global_store_dword v74, v54, s[18:19] offset:512
	global_store_dword v74, v50, s[18:19] offset:576
	s_add_u32 s18, s18, 0x2000
	s_addc_u32 s19, s19, 0
	global_store_dword v74, v63, s[18:19]
	global_store_dword v74, v59, s[18:19] offset:64
	global_store_dword v74, v55, s[18:19] offset:512
	global_store_dword v74, v51, s[18:19] offset:576
	s_add_u32 s18, s18, 0x2000
	s_addc_u32 s19, s19, 0
	global_store_dword v74, v64, s[18:19]
	global_store_dword v74, v60, s[18:19] offset:64
	global_store_dword v74, v56, s[18:19] offset:512
	global_store_dword v74, v52, s[18:19] offset:576
	s_add_u32 s18, s18, 0x2000
	s_addc_u32 s19, s19, 0
	global_store_dword v74, v65, s[18:19]
	global_store_dword v74, v61, s[18:19] offset:64
	global_store_dword v74, v57, s[18:19] offset:512
	global_store_dword v74, v53, s[18:19] offset:576
	s_add_u32 s18, s18, 0x1a000
	s_addc_u32 s19, s19, 0
	global_load_dword v88, v74, s[100:101]
	global_load_dword v89, v74, s[100:101] offset:64
	global_load_dword v90, v74, s[100:101] offset:512
	global_load_dword v91, v74, s[100:101] offset:576
	s_add_u32 s100, s100, 0x2000
	s_addc_u32 s101, s101, 0
	global_load_dword v92, v74, s[100:101]
	global_load_dword v93, v74, s[100:101] offset:64
	global_load_dword v94, v74, s[100:101] offset:512
	global_load_dword v95, v74, s[100:101] offset:576
	s_add_u32 s100, s100, 0x2000
	s_addc_u32 s101, s101, 0
	global_load_dword v96, v74, s[100:101]
	global_load_dword v97, v74, s[100:101] offset:64
	global_load_dword v152, v74, s[100:101] offset:512
	global_load_dword v153, v74, s[100:101] offset:576
	s_add_u32 s100, s100, 0x2000
	s_addc_u32 s101, s101, 0
	global_load_dword v154, v74, s[100:101]
	global_load_dword v155, v74, s[100:101] offset:64
	global_load_dword v162, v74, s[100:101] offset:512
	global_load_dword v163, v74, s[100:101] offset:576
	s_add_u32 s100, s100, 0x1a000
	s_addc_u32 s101, s101, 0
	s_waitcnt vmcnt(32)
	v_fma_f32 v46, v46, v76, v164
	v_fma_f32 v42, v42, v77, v165
	v_fma_f32 v38, v38, v86, v166
	v_fma_f32 v34, v34, v87, v167
	v_fma_f32 v47, v47, v76, v168
	v_fma_f32 v43, v43, v77, v169
	v_fma_f32 v39, v39, v86, v176
	v_fma_f32 v35, v35, v87, v177
	v_fma_f32 v48, v48, v76, v178
	v_fma_f32 v44, v44, v77, v179
	v_fma_f32 v40, v40, v86, v180
	v_fma_f32 v36, v36, v87, v181
	v_fma_f32 v49, v49, v76, v182
	v_fma_f32 v45, v45, v77, v183
	v_fma_f32 v41, v41, v86, v184
	v_fma_f32 v37, v37, v87, v185
	global_store_dword v74, v46, s[18:19]
	global_store_dword v74, v42, s[18:19] offset:64
	global_store_dword v74, v38, s[18:19] offset:512
	global_store_dword v74, v34, s[18:19] offset:576
	s_add_u32 s18, s18, 0x2000
	s_addc_u32 s19, s19, 0
	global_store_dword v74, v47, s[18:19]
	global_store_dword v74, v43, s[18:19] offset:64
	global_store_dword v74, v39, s[18:19] offset:512
	global_store_dword v74, v35, s[18:19] offset:576
	s_add_u32 s18, s18, 0x2000
	s_addc_u32 s19, s19, 0
	global_store_dword v74, v48, s[18:19]
	global_store_dword v74, v44, s[18:19] offset:64
	global_store_dword v74, v40, s[18:19] offset:512
	global_store_dword v74, v36, s[18:19] offset:576
	s_add_u32 s18, s18, 0x2000
	s_addc_u32 s19, s19, 0
	global_store_dword v74, v49, s[18:19]
	global_store_dword v74, v45, s[18:19] offset:64
	global_store_dword v74, v41, s[18:19] offset:512
	global_store_dword v74, v37, s[18:19] offset:576
	s_add_u32 s18, s18, 0x1a000
	s_addc_u32 s19, s19, 0
	global_load_dword v164, v74, s[100:101]
	global_load_dword v165, v74, s[100:101] offset:64
	global_load_dword v166, v74, s[100:101] offset:512
	global_load_dword v167, v74, s[100:101] offset:576
	s_add_u32 s100, s100, 0x2000
	s_addc_u32 s101, s101, 0
	global_load_dword v168, v74, s[100:101]
	global_load_dword v169, v74, s[100:101] offset:64
	global_load_dword v176, v74, s[100:101] offset:512
	global_load_dword v177, v74, s[100:101] offset:576
	s_add_u32 s100, s100, 0x2000
	s_addc_u32 s101, s101, 0
	global_load_dword v178, v74, s[100:101]
	global_load_dword v179, v74, s[100:101] offset:64
	global_load_dword v180, v74, s[100:101] offset:512
	global_load_dword v181, v74, s[100:101] offset:576
	s_add_u32 s100, s100, 0x2000
	s_addc_u32 s101, s101, 0
	global_load_dword v182, v74, s[100:101]
	global_load_dword v183, v74, s[100:101] offset:64
	global_load_dword v184, v74, s[100:101] offset:512
	global_load_dword v185, v74, s[100:101] offset:576
	s_waitcnt vmcnt(32)
;     __device__ __forceinline__ void operator()(const pg8::f32x4 (&acc)[2][2][4][2], const pg8::Unit& u, int wr, int wc, int fr, int fq) const {
;     ...
;         for (int ai = 0; ai < 2; ++ai)
; #pragma unroll
;             for (int m = 0; m < 4; ++m) { const size_t off = (size_t)(row0 + ai * 128 + m * 16) * D + col0;
; #pragma unroll
;                 for (int bj = 0; bj < 2; ++bj)
; #pragma unroll
;                     for (int n = 0; n < 2; ++n) { const pg8::f32x4 xv = *(const pg8::f32x4*)(xin + off + bj * 128 + n * 16);
;                         *(pg8::f32x4*)(xout + off + bj * 128 + n * 16) = xv + gv[bj][n] * acc[ai][bj][m][n]; }
;                 if (m & 1) asm volatile("" ::: "memory"); }
	v_fma_f32 v30, v30, v76, v88
	v_fma_f32 v26, v26, v77, v89
	v_fma_f32 v22, v22, v86, v90
	v_fma_f32 v18, v18, v87, v91
	v_fma_f32 v31, v31, v76, v92
	v_fma_f32 v27, v27, v77, v93
	v_fma_f32 v23, v23, v86, v94
	v_fma_f32 v19, v19, v87, v95
	v_fma_f32 v32, v32, v76, v96
	v_fma_f32 v28, v28, v77, v97
	v_fma_f32 v24, v24, v86, v152
	v_fma_f32 v20, v20, v87, v153
	v_fma_f32 v33, v33, v76, v154
	v_fma_f32 v29, v29, v77, v155
	v_fma_f32 v25, v25, v86, v162
	v_fma_f32 v21, v21, v87, v163
	global_store_dword v74, v30, s[18:19]
	global_store_dword v74, v26, s[18:19] offset:64
	global_store_dword v74, v22, s[18:19] offset:512
	global_store_dword v74, v18, s[18:19] offset:576
	s_add_u32 s18, s18, 0x2000
	s_addc_u32 s19, s19, 0
	global_store_dword v74, v31, s[18:19]
	global_store_dword v74, v27, s[18:19] offset:64
	global_store_dword v74, v23, s[18:19] offset:512
	global_store_dword v74, v19, s[18:19] offset:576
	s_add_u32 s18, s18, 0x2000
	s_addc_u32 s19, s19, 0
	global_store_dword v74, v32, s[18:19]
	global_store_dword v74, v28, s[18:19] offset:64
	global_store_dword v74, v24, s[18:19] offset:512
	global_store_dword v74, v20, s[18:19] offset:576
	s_add_u32 s18, s18, 0x2000
	s_addc_u32 s19, s19, 0
	global_store_dword v74, v33, s[18:19]
	global_store_dword v74, v29, s[18:19] offset:64
	global_store_dword v74, v25, s[18:19] offset:512
	global_store_dword v74, v21, s[18:19] offset:576
	s_add_u32 s18, s18, 0x1a000
	s_addc_u32 s19, s19, 0
	s_waitcnt vmcnt(16)
	v_fma_f32 v14, v14, v76, v164
	v_fma_f32 v10, v10, v77, v165
	v_fma_f32 v6, v6, v86, v166
	v_fma_f32 v2, v2, v87, v167
	v_fma_f32 v15, v15, v76, v168
	v_fma_f32 v11, v11, v77, v169
	v_fma_f32 v7, v7, v86, v176
	v_fma_f32 v3, v3, v87, v177
	v_fma_f32 v16, v16, v76, v178
	v_fma_f32 v12, v12, v77, v179
	v_fma_f32 v8, v8, v86, v180
	v_fma_f32 v4, v4, v87, v181
	v_fma_f32 v17, v17, v76, v182
	v_fma_f32 v13, v13, v77, v183
	v_fma_f32 v9, v9, v86, v184
	v_fma_f32 v5, v5, v87, v185
	global_store_dword v74, v14, s[18:19]
	global_store_dword v74, v10, s[18:19] offset:64
	global_store_dword v74, v6, s[18:19] offset:512
	global_store_dword v74, v2, s[18:19] offset:576
	s_add_u32 s18, s18, 0x2000
	s_addc_u32 s19, s19, 0
	global_store_dword v74, v15, s[18:19]
	global_store_dword v74, v11, s[18:19] offset:64
	global_store_dword v74, v7, s[18:19] offset:512
	global_store_dword v74, v3, s[18:19] offset:576
	s_add_u32 s18, s18, 0x2000
	s_addc_u32 s19, s19, 0
	global_store_dword v74, v16, s[18:19]
	global_store_dword v74, v12, s[18:19] offset:64
	global_store_dword v74, v8, s[18:19] offset:512
	global_store_dword v74, v4, s[18:19] offset:576
	s_add_u32 s18, s18, 0x2000
	s_addc_u32 s19, s19, 0
	global_store_dword v74, v17, s[18:19]
	global_store_dword v74, v13, s[18:19] offset:64
	global_store_dword v74, v9, s[18:19] offset:512
	global_store_dword v74, v5, s[18:19] offset:576
	s_mov_b64 s[18:19], -1
	s_andn2_b64 vcc, exec, s[40:41]
	s_cbranch_vccnz .LBB0_1666
	s_andn2_b64 vcc, exec, s[0:1]
	s_cbranch_vccnz .LBB0_1665
	s_barrier
	s_branch .LBB0_1665

; #define PG8_STAGE(bufoff, gbase, voff) do { _Pragma("unroll") for (int _i = 0; _i < 2; ++_i) \
;         __builtin_amdgcn_global_load_lds((const unsigned*)((const char*)(gbase) + (voff)[_i]), (PG8_LAS unsigned*)(lds + (bufoff) + ldsw + _i * 8192), 16, 0, 0); } while (0)
; #define PG8_LDA(dst, b, h) do { _Pragma("unroll") for (int m = 0; m < 4; ++m) _Pragma("unroll") for (int k = 0; k < 2; ++k) dst[m][k] = *(const PG8_LAS bf16x8*)(lds + PG8_SA(b, h) + aoff + m * 2048 + k * 1024); } while (0)
; #define PG8_LDB(dst, b, h) do { _Pragma("unroll") for (int n = 0; n < 2; ++n) _Pragma("unroll") for (int k = 0; k < 2; ++k) dst[n][k] = *(const PG8_LAS bf16x8*)(lds + PG8_SB(b, h) + boff + n * 2048 + k * 1024); } while (0)
; #define PG8_MMA(ai, bj, At, Bt) do { __builtin_amdgcn_s_setprio(1); _Pragma("unroll") for (int m = 0; m < 4; ++m) _Pragma("unroll") for (int n = 0; n < 2; ++n) _Pragma("unroll") for (int k = 0; k < 2; ++k) \
;         acc[ai][bj][m][n] = __builtin_amdgcn_mfma_f32_16x16x32_bf16(Bt[n][k], At[m][k], acc[ai][bj][m][n], 0, 0, 0); __builtin_amdgcn_s_setprio(0); } while (0)
; template <class Epi, class Sched, bool ALIGN_EPI = false, bool SP2 = false>
; __device__ __forceinline__ void gemm_phase(PG8_LAS unsigned char* lds, const Gemm g, const Sched& S, const Epi& E, int wave_s) {
;     ...
;         for (int t = 0; t < nt; t += 2) {
;             const bool last = (t == nt - 2);
;             const char* a1 = cA + (size_t)(t + 1) * kstep;
;             const char* a2 = last ? nA : cA + (size_t)(t + 2) * kstep; const char* b2 = last ? nB : cB + (size_t)(t + 2) * kstep;
;             const char* a3 = a2 + kstep; const char* b3 = b2 + kstep;
;             if (last && has_next) S.a_ready(nxt);
;             if constexpr (Epi::HAS_MID) { if (t == nt / 2) E.mid(acc, cur, wr, wc, fr, fq); }
;             if constexpr (SP2) {
;             PG8_LDB(B0, 0, 0); PG8_LDB(B1, 0, 1); PG8_SCHED; PG8_LDA(At, 0, 0); PG8_STAGE(PG8_SA(1, 1), a1 + hstepA, voffA);
;             PG8_WAIT_V(8); PG8_WAIT_L(0); PG8_BAR; PG8_MMA(0, 0, At, B0); PG8_MMA(0, 1, At, B1); PG8_BAR; PG8_SCHED;
;             PG8_LDA(At, 0, 1); PG8_STAGE(PG8_SB(0, 0), b2, voffB); PG8_STAGE(PG8_SB(0, 1), b2 + hstepB, voffB); PG8_STAGE(PG8_SA(0, 0), a2, voffA);
;             PG8_WAIT_V(8); PG8_WAIT_L(0); PG8_BAR; PG8_MMA(1, 0, At, B0); PG8_MMA(1, 1, At, B1); PG8_BAR; PG8_SCHED;
.LBB0_1870:
	s_add_u32 s16, s14, 0x100
	s_addc_u32 s17, s15, 0
	s_add_i32 s34, 0, 0x10000
	s_cmpk_eq_i32 s39, 0x54
	s_cselect_b32 s21, s11, s17
	s_cselect_b32 s20, s10, s16
	s_cselect_b32 s19, s13, s38
	s_cselect_b32 s18, s12, s27
	s_add_i32 s35, 0, 0x14000
	v_add_u32_e32 v148, s34, v159
	v_add_u32_e32 v156, s35, v159
	ds_read_b128 v[136:139], v148
	ds_read_b128 v[140:143], v148 offset:1024
	ds_read_b128 v[144:147], v148 offset:2048
	ds_read_b128 v[148:151], v148 offset:3072
	ds_read_b128 v[152:155], v156
	ds_read_b128 v[162:165], v156 offset:1024
	ds_read_b128 v[166:169], v156 offset:2048
	ds_read_b128 v[176:179], v156 offset:3072
	v_lshl_add_u64 v[156:157], s[14:15], 0, v[134:135]
	s_add_i32 m0, s33, 0xc000
	ds_read_b128 v[180:183], v161
	ds_read_b128 v[184:187], v161 offset:1024
	ds_read_b128 v[188:191], v161 offset:2048
	ds_read_b128 v[192:195], v161 offset:3072
	ds_read_b128 v[196:199], v161 offset:4096
	ds_read_b128 v[208:211], v161 offset:5120
	ds_read_b128 v[212:215], v161 offset:6144
	ds_read_b128 v[216:219], v161 offset:7168
	global_load_lds_dwordx4 v[156:157], off
	v_lshl_add_u64 v[156:157], s[14:15], 0, v[132:133]
	s_add_i32 m0, s33, 0xe000
	s_nop 0
	global_load_lds_dwordx4 v[156:157], off
	s_waitcnt vmcnt(8)
	s_waitcnt lgkmcnt(0)
	s_barrier
	s_setprio 1
	s_waitcnt lgkmcnt(0)
	v_mfma_f32_16x16x32_bf16 v[126:129], v[180:183], v[136:139], v[126:129]
	v_mfma_f32_16x16x32_bf16 v[122:125], v[180:183], v[144:147], v[122:125]
	v_mfma_f32_16x16x32_bf16 v[110:113], v[188:191], v[136:139], v[110:113]
	v_mfma_f32_16x16x32_bf16 v[106:109], v[188:191], v[144:147], v[106:109]
	v_mfma_f32_16x16x32_bf16 v[94:97], v[196:199], v[136:139], v[94:97]
	v_mfma_f32_16x16x32_bf16 v[90:93], v[196:199], v[144:147], v[90:93]
	v_mfma_f32_16x16x32_bf16 v[78:81], v[212:215], v[136:139], v[78:81]
	v_mfma_f32_16x16x32_bf16 v[74:77], v[212:215], v[144:147], v[74:77]
	v_mfma_f32_16x16x32_bf16 v[126:129], v[184:187], v[140:143], v[126:129]
	v_mfma_f32_16x16x32_bf16 v[122:125], v[184:187], v[148:151], v[122:125]
	v_mfma_f32_16x16x32_bf16 v[110:113], v[192:195], v[140:143], v[110:113]
	v_mfma_f32_16x16x32_bf16 v[106:109], v[192:195], v[148:151], v[106:109]
	v_mfma_f32_16x16x32_bf16 v[94:97], v[208:211], v[140:143], v[94:97]
	v_mfma_f32_16x16x32_bf16 v[90:93], v[208:211], v[148:151], v[90:93]
	v_mfma_f32_16x16x32_bf16 v[78:81], v[216:219], v[140:143], v[78:81]
	v_mfma_f32_16x16x32_bf16 v[74:77], v[216:219], v[148:151], v[74:77]
	s_setprio 0
	s_setprio 1
	v_mfma_f32_16x16x32_bf16 v[118:121], v[180:183], v[152:155], v[118:121]
	v_mfma_f32_16x16x32_bf16 v[114:117], v[180:183], v[166:169], v[114:117]
	v_mfma_f32_16x16x32_bf16 v[102:105], v[188:191], v[152:155], v[102:105]
	v_mfma_f32_16x16x32_bf16 v[98:101], v[188:191], v[166:169], v[98:101]
	v_mfma_f32_16x16x32_bf16 v[86:89], v[196:199], v[152:155], v[86:89]
	v_mfma_f32_16x16x32_bf16 v[82:85], v[196:199], v[166:169], v[82:85]
	v_mfma_f32_16x16x32_bf16 v[70:73], v[212:215], v[152:155], v[70:73]
	v_mfma_f32_16x16x32_bf16 v[66:69], v[212:215], v[166:169], v[66:69]
	v_mfma_f32_16x16x32_bf16 v[118:121], v[184:187], v[162:165], v[118:121]
	v_mfma_f32_16x16x32_bf16 v[114:117], v[184:187], v[176:179], v[114:117]
	v_mfma_f32_16x16x32_bf16 v[102:105], v[192:195], v[162:165], v[102:105]
	v_mfma_f32_16x16x32_bf16 v[98:101], v[192:195], v[176:179], v[98:101]
	v_mfma_f32_16x16x32_bf16 v[86:89], v[208:211], v[162:165], v[86:89]
	v_mfma_f32_16x16x32_bf16 v[82:85], v[208:211], v[176:179], v[82:85]
	v_mfma_f32_16x16x32_bf16 v[70:73], v[216:219], v[162:165], v[70:73]
	v_mfma_f32_16x16x32_bf16 v[66:69], v[216:219], v[176:179], v[66:69]
	s_setprio 0
	s_barrier
	s_add_i32 s14, s34, s40
	v_lshl_add_u64 v[156:157], s[18:19], 0, v[0:1]
	s_mov_b32 m0, s14
	ds_read_b128 v[180:183], v161 offset:16384
	ds_read_b128 v[184:187], v161 offset:17408
	ds_read_b128 v[188:191], v161 offset:18432
	ds_read_b128 v[192:195], v161 offset:19456
	ds_read_b128 v[196:199], v161 offset:20480
	ds_read_b128 v[208:211], v161 offset:21504
	ds_read_b128 v[212:215], v161 offset:22528
	ds_read_b128 v[216:219], v161 offset:23552
	global_load_lds_dwordx4 v[156:157], off
	s_add_i32 m0, s14, 0x2000
	s_add_u32 s14, s18, 0x160000
	v_lshl_add_u64 v[170:171], s[18:19], 0, v[130:131]
	s_addc_u32 s15, s19, 0
	s_add_i32 s34, s35, s40
	global_load_lds_dwordx4 v[170:171], off
	v_lshl_add_u64 v[200:201], s[14:15], 0, v[0:1]
	s_mov_b32 m0, s34
	v_lshl_add_u64 v[220:221], s[20:21], 0, v[130:131]
	global_load_lds_dwordx4 v[200:201], off
	v_lshl_add_u64 v[200:201], s[14:15], 0, v[130:131]
	s_add_i32 m0, s34, 0x2000
	s_nop 0
	global_load_lds_dwordx4 v[200:201], off
	v_lshl_add_u64 v[200:201], s[20:21], 0, v[0:1]
	s_mov_b32 m0, s33
	s_nop 0
	global_load_lds_dwordx4 v[200:201], off
	s_mov_b32 m0, s41
	s_nop 0
	global_load_lds_dwordx4 v[220:221], off
	s_waitcnt vmcnt(8)
	s_waitcnt lgkmcnt(0)
	s_barrier
; #define PG8_STAGE(bufoff, gbase, voff) do { _Pragma("unroll") for (int _i = 0; _i < 2; ++_i) \
;         __builtin_amdgcn_global_load_lds((const unsigned*)((const char*)(gbase) + (voff)[_i]), (PG8_LAS unsigned*)(lds + (bufoff) + ldsw + _i * 8192), 16, 0, 0); } while (0)
; #define PG8_LDA(dst, b, h) do { _Pragma("unroll") for (int m = 0; m < 4; ++m) _Pragma("unroll") for (int k = 0; k < 2; ++k) dst[m][k] = *(const PG8_LAS bf16x8*)(lds + PG8_SA(b, h) + aoff + m * 2048 + k * 1024); } while (0)
; #define PG8_LDB(dst, b, h) do { _Pragma("unroll") for (int n = 0; n < 2; ++n) _Pragma("unroll") for (int k = 0; k < 2; ++k) dst[n][k] = *(const PG8_LAS bf16x8*)(lds + PG8_SB(b, h) + boff + n * 2048 + k * 1024); } while (0)
; #define PG8_MMA(ai, bj, At, Bt) do { __builtin_amdgcn_s_setprio(1); _Pragma("unroll") for (int m = 0; m < 4; ++m) _Pragma("unroll") for (int n = 0; n < 2; ++n) _Pragma("unroll") for (int k = 0; k < 2; ++k) \
;         acc[ai][bj][m][n] = __builtin_amdgcn_mfma_f32_16x16x32_bf16(Bt[n][k], At[m][k], acc[ai][bj][m][n], 0, 0, 0); __builtin_amdgcn_s_setprio(0); } while (0)
; #define PG8_WAIT_V(n) asm volatile("s_waitcnt vmcnt(" #n ")" ::: "memory")
; #define PG8_WAIT_L(n) asm volatile("s_waitcnt lgkmcnt(" #n ")" ::: "memory")
; #define PG8_BAR __builtin_amdgcn_s_barrier()
; #define PG8_SCHED __builtin_amdgcn_sched_barrier(0)
; template <class Epi, class Sched, bool ALIGN_EPI = false, bool SP2 = false>
; __device__ __forceinline__ void gemm_phase(PG8_LAS unsigned char* lds, const Gemm g, const Sched& S, const Epi& E, int wave_s) {
;     ...
;             PG8_WAIT_V(8); PG8_WAIT_L(0); PG8_BAR; PG8_MMA(1, 0, At, B0); PG8_MMA(1, 1, At, B1); PG8_BAR; PG8_SCHED;
;             PG8_LDB(B0, 1, 0); PG8_LDB(B1, 1, 1); PG8_SCHED; PG8_LDA(At, 1, 0); PG8_STAGE(PG8_SA(0, 1), a2 + hstepA, voffA);
;             PG8_WAIT_V(8); PG8_WAIT_L(0); PG8_BAR; PG8_MMA(0, 0, At, B0); PG8_MMA(0, 1, At, B1); PG8_BAR; PG8_SCHED;
	s_setprio 1
	s_waitcnt lgkmcnt(0)
	v_mfma_f32_16x16x32_bf16 v[62:65], v[180:183], v[136:139], v[62:65]
	v_mfma_f32_16x16x32_bf16 v[58:61], v[180:183], v[144:147], v[58:61]
	v_mfma_f32_16x16x32_bf16 v[46:49], v[188:191], v[136:139], v[46:49]
	v_mfma_f32_16x16x32_bf16 v[42:45], v[188:191], v[144:147], v[42:45]
	v_mfma_f32_16x16x32_bf16 v[30:33], v[196:199], v[136:139], v[30:33]
	v_mfma_f32_16x16x32_bf16 v[26:29], v[196:199], v[144:147], v[26:29]
	v_mfma_f32_16x16x32_bf16 v[14:17], v[212:215], v[136:139], v[14:17]
	v_mfma_f32_16x16x32_bf16 v[10:13], v[212:215], v[144:147], v[10:13]
	v_mfma_f32_16x16x32_bf16 v[62:65], v[184:187], v[140:143], v[62:65]
	v_mfma_f32_16x16x32_bf16 v[58:61], v[184:187], v[148:151], v[58:61]
	v_mfma_f32_16x16x32_bf16 v[46:49], v[192:195], v[140:143], v[46:49]
	v_mfma_f32_16x16x32_bf16 v[42:45], v[192:195], v[148:151], v[42:45]
	v_mfma_f32_16x16x32_bf16 v[30:33], v[208:211], v[140:143], v[30:33]
	v_mfma_f32_16x16x32_bf16 v[26:29], v[208:211], v[148:151], v[26:29]
	v_mfma_f32_16x16x32_bf16 v[14:17], v[216:219], v[140:143], v[14:17]
	v_mfma_f32_16x16x32_bf16 v[10:13], v[216:219], v[148:151], v[10:13]
	s_setprio 0
	s_setprio 1
	v_mfma_f32_16x16x32_bf16 v[54:57], v[180:183], v[152:155], v[54:57]
	v_mfma_f32_16x16x32_bf16 v[50:53], v[180:183], v[166:169], v[50:53]
	v_mfma_f32_16x16x32_bf16 v[38:41], v[188:191], v[152:155], v[38:41]
	v_mfma_f32_16x16x32_bf16 v[34:37], v[188:191], v[166:169], v[34:37]
	v_mfma_f32_16x16x32_bf16 v[22:25], v[196:199], v[152:155], v[22:25]
	v_mfma_f32_16x16x32_bf16 v[18:21], v[196:199], v[166:169], v[18:21]
	v_mfma_f32_16x16x32_bf16 v[6:9], v[212:215], v[152:155], v[6:9]
	v_mfma_f32_16x16x32_bf16 v[2:5], v[212:215], v[166:169], v[2:5]
	v_mfma_f32_16x16x32_bf16 v[54:57], v[184:187], v[162:165], v[54:57]
	v_mfma_f32_16x16x32_bf16 v[50:53], v[184:187], v[176:179], v[50:53]
	v_mfma_f32_16x16x32_bf16 v[38:41], v[192:195], v[162:165], v[38:41]
	v_mfma_f32_16x16x32_bf16 v[34:37], v[192:195], v[176:179], v[34:37]
	v_mfma_f32_16x16x32_bf16 v[22:25], v[208:211], v[162:165], v[22:25]
	v_mfma_f32_16x16x32_bf16 v[18:21], v[208:211], v[176:179], v[18:21]
	v_mfma_f32_16x16x32_bf16 v[6:9], v[216:219], v[162:165], v[6:9]
	v_mfma_f32_16x16x32_bf16 v[2:5], v[216:219], v[176:179], v[2:5]
	s_setprio 0
	s_barrier
	s_add_i32 s34, 0, 0x18000
	s_add_i32 s35, 0, 0x1c000
	v_add_u32_e32 v148, s34, v159
	v_add_u32_e32 v176, s35, v159
	ds_read_b128 v[136:139], v148
	ds_read_b128 v[140:143], v148 offset:1024
	ds_read_b128 v[144:147], v148 offset:2048
	ds_read_b128 v[148:151], v148 offset:3072
	ds_read_b128 v[152:155], v176
	ds_read_b128 v[162:165], v176 offset:1024
	ds_read_b128 v[166:169], v176 offset:2048
	ds_read_b128 v[176:179], v176 offset:3072
	s_add_u32 s14, s20, 0x160000
	s_addc_u32 s15, s21, 0
	s_mov_b32 m0, s42
	v_lshl_add_u64 v[222:223], s[14:15], 0, v[0:1]
	ds_read_b128 v[180:183], v161 offset:32768
	ds_read_b128 v[184:187], v161 offset:33792
	ds_read_b128 v[188:191], v161 offset:34816
	ds_read_b128 v[192:195], v161 offset:35840
	ds_read_b128 v[196:199], v161 offset:36864
	ds_read_b128 v[208:211], v161 offset:37888
	ds_read_b128 v[212:215], v161 offset:38912
	ds_read_b128 v[216:219], v161 offset:39936
	global_load_lds_dwordx4 v[222:223], off
	v_lshl_add_u64 v[222:223], s[14:15], 0, v[130:131]
	s_mov_b32 m0, s43
	s_nop 0
	global_load_lds_dwordx4 v[222:223], off
	s_waitcnt vmcnt(8)
	s_waitcnt lgkmcnt(0)
	s_barrier
	s_setprio 1
	s_waitcnt lgkmcnt(0)
	v_mfma_f32_16x16x32_bf16 v[126:129], v[180:183], v[136:139], v[126:129]
	v_mfma_f32_16x16x32_bf16 v[122:125], v[180:183], v[144:147], v[122:125]
	v_mfma_f32_16x16x32_bf16 v[110:113], v[188:191], v[136:139], v[110:113]
	v_mfma_f32_16x16x32_bf16 v[106:109], v[188:191], v[144:147], v[106:109]
	v_mfma_f32_16x16x32_bf16 v[94:97], v[196:199], v[136:139], v[94:97]
	v_mfma_f32_16x16x32_bf16 v[90:93], v[196:199], v[144:147], v[90:93]
	v_mfma_f32_16x16x32_bf16 v[78:81], v[212:215], v[136:139], v[78:81]
	v_mfma_f32_16x16x32_bf16 v[74:77], v[212:215], v[144:147], v[74:77]
	v_mfma_f32_16x16x32_bf16 v[126:129], v[184:187], v[140:143], v[126:129]
	v_mfma_f32_16x16x32_bf16 v[122:125], v[184:187], v[148:151], v[122:125]
	v_mfma_f32_16x16x32_bf16 v[110:113], v[192:195], v[140:143], v[110:113]
	v_mfma_f32_16x16x32_bf16 v[106:109], v[192:195], v[148:151], v[106:109]
	v_mfma_f32_16x16x32_bf16 v[94:97], v[208:211], v[140:143], v[94:97]
	v_mfma_f32_16x16x32_bf16 v[90:93], v[208:211], v[148:151], v[90:93]
	v_mfma_f32_16x16x32_bf16 v[78:81], v[216:219], v[140:143], v[78:81]
	v_mfma_f32_16x16x32_bf16 v[74:77], v[216:219], v[148:151], v[74:77]
	s_setprio 0
	s_setprio 1
	v_mfma_f32_16x16x32_bf16 v[118:121], v[180:183], v[152:155], v[118:121]
	v_mfma_f32_16x16x32_bf16 v[114:117], v[180:183], v[166:169], v[114:117]
	v_mfma_f32_16x16x32_bf16 v[102:105], v[188:191], v[152:155], v[102:105]
	v_mfma_f32_16x16x32_bf16 v[98:101], v[188:191], v[166:169], v[98:101]
	v_mfma_f32_16x16x32_bf16 v[86:89], v[196:199], v[152:155], v[86:89]
	v_mfma_f32_16x16x32_bf16 v[82:85], v[196:199], v[166:169], v[82:85]
	v_mfma_f32_16x16x32_bf16 v[70:73], v[212:215], v[152:155], v[70:73]
	v_mfma_f32_16x16x32_bf16 v[66:69], v[212:215], v[166:169], v[66:69]
	v_mfma_f32_16x16x32_bf16 v[118:121], v[184:187], v[162:165], v[118:121]
	v_mfma_f32_16x16x32_bf16 v[114:117], v[184:187], v[176:179], v[114:117]
	v_mfma_f32_16x16x32_bf16 v[102:105], v[192:195], v[162:165], v[102:105]
	v_mfma_f32_16x16x32_bf16 v[98:101], v[192:195], v[176:179], v[98:101]
	v_mfma_f32_16x16x32_bf16 v[86:89], v[208:211], v[162:165], v[86:89]
	v_mfma_f32_16x16x32_bf16 v[82:85], v[208:211], v[176:179], v[82:85]
	v_mfma_f32_16x16x32_bf16 v[70:73], v[216:219], v[162:165], v[70:73]
	v_mfma_f32_16x16x32_bf16 v[66:69], v[216:219], v[176:179], v[66:69]
	s_setprio 0
	s_barrier
; #define PG8_STAGE(bufoff, gbase, voff) do { _Pragma("unroll") for (int _i = 0; _i < 2; ++_i) \
;         __builtin_amdgcn_global_load_lds((const unsigned*)((const char*)(gbase) + (voff)[_i]), (PG8_LAS unsigned*)(lds + (bufoff) + ldsw + _i * 8192), 16, 0, 0); } while (0)
; #define PG8_LDA(dst, b, h) do { _Pragma("unroll") for (int m = 0; m < 4; ++m) _Pragma("unroll") for (int k = 0; k < 2; ++k) dst[m][k] = *(const PG8_LAS bf16x8*)(lds + PG8_SA(b, h) + aoff + m * 2048 + k * 1024); } while (0)
; #define PG8_MMA(ai, bj, At, Bt) do { __builtin_amdgcn_s_setprio(1); _Pragma("unroll") for (int m = 0; m < 4; ++m) _Pragma("unroll") for (int n = 0; n < 2; ++n) _Pragma("unroll") for (int k = 0; k < 2; ++k) \
;         acc[ai][bj][m][n] = __builtin_amdgcn_mfma_f32_16x16x32_bf16(Bt[n][k], At[m][k], acc[ai][bj][m][n], 0, 0, 0); __builtin_amdgcn_s_setprio(0); } while (0)
; #define PG8_WAIT_V(n) asm volatile("s_waitcnt vmcnt(" #n ")" ::: "memory")
; #define PG8_BAR __builtin_amdgcn_s_barrier()
; template <class Epi, class Sched, bool ALIGN_EPI = false, bool SP2 = false>
; __device__ __forceinline__ void gemm_phase(PG8_LAS unsigned char* lds, const Gemm g, const Sched& S, const Epi& E, int wave_s) {
;     ...
;             PG8_LDA(At, 1, 1); PG8_STAGE(PG8_SB(1, 0), b3, voffB); PG8_STAGE(PG8_SB(1, 1), b3 + hstepB, voffB); PG8_STAGE(PG8_SA(1, 0), a3, voffA);
;             PG8_WAIT_V(8); PG8_WAIT_L(0); PG8_BAR; PG8_MMA(1, 0, At, B0); PG8_MMA(1, 1, At, B1); PG8_BAR; PG8_SCHED;
;     __device__ __forceinline__ void operator()(const pg8::f32x4 (&acc)[2][2][4][2], const pg8::Unit& u, int wr, int wc, int fr, int fq) const {
;         const int b = u.pm >> 4;
;         const int row0 = u.pm * 256 + wr * 64 + fr, col0 = u.pn * 256 + wc * 32 + 4 * fq;
;         pg8::f32x4 gv[2][2];
; #pragma unroll
;         for (int bj = 0; bj < 2; ++bj)
; #pragma unroll
;             for (int n = 0; n < 2; ++n) gv[bj][n] = *(const pg8::f32x4*)(gate + (size_t)b * NMOD + col0 + bj * 128 + n * 16) * coef;
; #pragma unroll
;         for (int ai = 0; ai < 2; ++ai)
; #pragma unroll
;             for (int m = 0; m < 4; ++m) { const size_t off = (size_t)(row0 + ai * 128 + m * 16) * D + col0;
; #pragma unroll
;                 for (int bj = 0; bj < 2; ++bj)
; #pragma unroll
;                     for (int n = 0; n < 2; ++n) { const pg8::f32x4 xv = *(const pg8::f32x4*)(xin + off + bj * 128 + n * 16);
	s_add_i32 s14, s34, s40
	v_lshl_add_u64 v[156:157], v[156:157], 0, s[30:31]
	s_mov_b32 m0, s14
	ds_read_b128 v[180:183], v161 offset:49152
	ds_read_b128 v[184:187], v161 offset:50176
	ds_read_b128 v[188:191], v161 offset:51200
	ds_read_b128 v[192:195], v161 offset:52224
	ds_read_b128 v[196:199], v161 offset:53248
	ds_read_b128 v[208:211], v161 offset:54272
	ds_read_b128 v[212:215], v161 offset:55296
	ds_read_b128 v[216:219], v161 offset:56320
	global_load_lds_dwordx4 v[156:157], off
	s_add_i32 m0, s14, 0x2000
	s_add_u32 s14, s18, 0x160080
	v_lshl_add_u64 v[156:157], v[170:171], 0, s[30:31]
	s_addc_u32 s15, s19, 0
	s_add_i32 s18, s35, s40
	global_load_lds_dwordx4 v[156:157], off
	v_lshl_add_u64 v[156:157], s[14:15], 0, v[0:1]
	s_mov_b32 m0, s18
	s_nop 0
	global_load_lds_dwordx4 v[156:157], off
	v_lshl_add_u64 v[156:157], s[14:15], 0, v[130:131]
	s_add_i32 m0, s18, 0x2000
	s_nop 0
	global_load_lds_dwordx4 v[156:157], off
	v_lshl_add_u64 v[156:157], v[200:201], 0, s[30:31]
	s_mov_b32 m0, s46
	s_nop 0
	global_load_lds_dwordx4 v[156:157], off
	v_lshl_add_u64 v[156:157], v[220:221], 0, s[30:31]
	s_mov_b32 m0, s47
	s_nop 0
	global_load_lds_dwordx4 v[156:157], off
	s_waitcnt vmcnt(8)
	s_waitcnt lgkmcnt(0)
	s_barrier
	s_setprio 1
	s_waitcnt lgkmcnt(0)
	v_mfma_f32_16x16x32_bf16 v[62:65], v[180:183], v[136:139], v[62:65]
	v_mfma_f32_16x16x32_bf16 v[58:61], v[180:183], v[144:147], v[58:61]
	v_mfma_f32_16x16x32_bf16 v[46:49], v[188:191], v[136:139], v[46:49]
	v_mfma_f32_16x16x32_bf16 v[42:45], v[188:191], v[144:147], v[42:45]
	v_mfma_f32_16x16x32_bf16 v[30:33], v[196:199], v[136:139], v[30:33]
	v_mfma_f32_16x16x32_bf16 v[26:29], v[196:199], v[144:147], v[26:29]
	v_mfma_f32_16x16x32_bf16 v[14:17], v[212:215], v[136:139], v[14:17]
	v_mfma_f32_16x16x32_bf16 v[10:13], v[212:215], v[144:147], v[10:13]
	v_mfma_f32_16x16x32_bf16 v[62:65], v[184:187], v[140:143], v[62:65]
	v_mfma_f32_16x16x32_bf16 v[58:61], v[184:187], v[148:151], v[58:61]
	v_mfma_f32_16x16x32_bf16 v[46:49], v[192:195], v[140:143], v[46:49]
	v_mfma_f32_16x16x32_bf16 v[42:45], v[192:195], v[148:151], v[42:45]
	v_mfma_f32_16x16x32_bf16 v[30:33], v[208:211], v[140:143], v[30:33]
	v_mfma_f32_16x16x32_bf16 v[26:29], v[208:211], v[148:151], v[26:29]
	v_mfma_f32_16x16x32_bf16 v[14:17], v[216:219], v[140:143], v[14:17]
	v_mfma_f32_16x16x32_bf16 v[10:13], v[216:219], v[148:151], v[10:13]
	s_setprio 0
	s_setprio 1
	v_mfma_f32_16x16x32_bf16 v[54:57], v[180:183], v[152:155], v[54:57]
	v_mfma_f32_16x16x32_bf16 v[50:53], v[180:183], v[166:169], v[50:53]
	v_mfma_f32_16x16x32_bf16 v[38:41], v[188:191], v[152:155], v[38:41]
	v_mfma_f32_16x16x32_bf16 v[34:37], v[188:191], v[166:169], v[34:37]
	v_mfma_f32_16x16x32_bf16 v[22:25], v[196:199], v[152:155], v[22:25]
	v_mfma_f32_16x16x32_bf16 v[18:21], v[196:199], v[166:169], v[18:21]
	v_mfma_f32_16x16x32_bf16 v[6:9], v[212:215], v[152:155], v[6:9]
	v_mfma_f32_16x16x32_bf16 v[2:5], v[212:215], v[166:169], v[2:5]
	v_mfma_f32_16x16x32_bf16 v[54:57], v[184:187], v[162:165], v[54:57]
	v_mfma_f32_16x16x32_bf16 v[50:53], v[184:187], v[176:179], v[50:53]
	v_mfma_f32_16x16x32_bf16 v[38:41], v[192:195], v[162:165], v[38:41]
	v_mfma_f32_16x16x32_bf16 v[34:37], v[192:195], v[176:179], v[34:37]
	v_mfma_f32_16x16x32_bf16 v[22:25], v[208:211], v[162:165], v[22:25]
	v_mfma_f32_16x16x32_bf16 v[18:21], v[208:211], v[176:179], v[18:21]
	v_mfma_f32_16x16x32_bf16 v[6:9], v[216:219], v[162:165], v[6:9]
	v_mfma_f32_16x16x32_bf16 v[2:5], v[216:219], v[176:179], v[2:5]
	s_setprio 0
	s_barrier
	s_add_i32 s39, s39, 2
	s_add_u32 s27, s27, 0x100
	s_addc_u32 s38, s38, 0
	s_cmpk_gt_u32 s39, 0x55
	s_mov_b64 s[14:15], s[16:17]
	s_cbranch_scc0 .LBB0_1870
	s_and_b64 vcc, exec, s[8:9]
	s_cbranch_vccz .LBB0_1873
	s_barrier
.LBB0_1873:
	v_and_b32_e32 v136, 0x40, v158
	v_and_b32_e32 v137, 12, v160
	v_or_b32_e32 v136, v136, v137
	v_and_b32_e32 v137, 0x60, v160
	v_and_or_b32 v137, v158, 15, v137
	v_lshlrev_b32_e32 v137, 2, v137
	v_lshl_add_u32 v136, v136, 13, v137
	s_ashr_i32 vcc_hi, s51, 4
	s_mul_i32 vcc_hi, vcc_hi, 0x12000
	s_lshl_b32 vcc_lo, s26, 10
	s_add_u32 vcc_hi, vcc_hi, vcc_lo
	s_add_u32 s14, s44, vcc_hi
	s_addc_u32 s15, s45, 0
	global_load_dword v138, v137, s[14:15]
	global_load_dword v139, v137, s[14:15] offset:64
	global_load_dword v140, v137, s[14:15] offset:512
	global_load_dword v141, v137, s[14:15] offset:576
	s_lshl_b32 vcc_hi, s51, 21
	s_add_u32 vcc_lo, vcc_lo, vcc_hi
	s_add_u32 s100, s6, vcc_lo
	s_addc_u32 s101, s7, 0
	s_add_u32 s14, s6, vcc_lo
	s_addc_u32 s15, s7, 0
	global_load_dword v142, v136, s[100:101]
	global_load_dword v143, v136, s[100:101] offset:64
	global_load_dword v144, v136, s[100:101] offset:512
	global_load_dword v145, v136, s[100:101] offset:576
	s_add_u32 s100, s100, 0x2000
	s_addc_u32 s101, s101, 0
	global_load_dword v146, v136, s[100:101]
	global_load_dword v147, v136, s[100:101] offset:64
	global_load_dword v148, v136, s[100:101] offset:512
	global_load_dword v149, v136, s[100:101] offset:576
	s_add_u32 s100, s100, 0x2000
	s_addc_u32 s101, s101, 0
	global_load_dword v150, v136, s[100:101]
	global_load_dword v151, v136, s[100:101] offset:64
	global_load_dword v152, v136, s[100:101] offset:512
	global_load_dword v153, v136, s[100:101] offset:576
	s_add_u32 s100, s100, 0x2000
	s_addc_u32 s101, s101, 0
	global_load_dword v154, v136, s[100:101]
	global_load_dword v155, v136, s[100:101] offset:64
	global_load_dword v162, v136, s[100:101] offset:512
	global_load_dword v163, v136, s[100:101] offset:576
	s_add_u32 s100, s100, 0x1a000
	s_addc_u32 s101, s101, 0
	global_load_dword v164, v136, s[100:101]
	global_load_dword v165, v136, s[100:101] offset:64
	global_load_dword v166, v136, s[100:101] offset:512
	global_load_dword v167, v136, s[100:101] offset:576
	s_add_u32 s100, s100, 0x2000
	s_addc_u32 s101, s101, 0
	global_load_dword v168, v136, s[100:101]
	global_load_dword v169, v136, s[100:101] offset:64
	global_load_dword v176, v136, s[100:101] offset:512
	global_load_dword v177, v136, s[100:101] offset:576
	s_add_u32 s100, s100, 0x2000
	s_addc_u32 s101, s101, 0
	global_load_dword v178, v136, s[100:101]
	global_load_dword v179, v136, s[100:101] offset:64
	global_load_dword v180, v136, s[100:101] offset:512
	global_load_dword v181, v136, s[100:101] offset:576
	s_add_u32 s100, s100, 0x2000
	s_addc_u32 s101, s101, 0
	global_load_dword v182, v136, s[100:101]
	global_load_dword v183, v136, s[100:101] offset:64
	global_load_dword v184, v136, s[100:101] offset:512
	global_load_dword v185, v136, s[100:101] offset:576
	s_add_u32 s100, s100, 0x1a000
	s_addc_u32 s101, s101, 0
	s_waitcnt vmcnt(16)
;     __device__ __forceinline__ void operator()(const pg8::f32x4 (&acc)[2][2][4][2], const pg8::Unit& u, int wr, int wc, int fr, int fq) const {
;     ...
;         for (int ai = 0; ai < 2; ++ai)
; #pragma unroll
;             for (int m = 0; m < 4; ++m) { const size_t off = (size_t)(row0 + ai * 128 + m * 16) * D + col0;
; #pragma unroll
;                 for (int bj = 0; bj < 2; ++bj)
; #pragma unroll
;                     for (int n = 0; n < 2; ++n) { const pg8::f32x4 xv = *(const pg8::f32x4*)(xin + off + bj * 128 + n * 16);
;                         *(pg8::f32x4*)(xout + off + bj * 128 + n * 16) = xv + gv[bj][n] * acc[ai][bj][m][n]; }
;                 if (m & 1) asm volatile("" ::: "memory"); }
	v_mul_f32_e32 v138, 0.5, v138
	v_mul_f32_e32 v139, 0.5, v139
	v_mul_f32_e32 v140, 0.5, v140
	v_mul_f32_e32 v141, 0.5, v141
	v_fma_f32 v126, v126, v138, v142
	v_fma_f32 v122, v122, v139, v143
	v_fma_f32 v118, v118, v140, v144
	v_fma_f32 v114, v114, v141, v145
	v_fma_f32 v127, v127, v138, v146
	v_fma_f32 v123, v123, v139, v147
	v_fma_f32 v119, v119, v140, v148
	v_fma_f32 v115, v115, v141, v149
	v_fma_f32 v128, v128, v138, v150
	v_fma_f32 v124, v124, v139, v151
	v_fma_f32 v120, v120, v140, v152
	v_fma_f32 v116, v116, v141, v153
	v_fma_f32 v129, v129, v138, v154
	v_fma_f32 v125, v125, v139, v155
	v_fma_f32 v121, v121, v140, v162
	v_fma_f32 v117, v117, v141, v163
	global_store_dword v136, v126, s[14:15]
	global_store_dword v136, v122, s[14:15] offset:64
	global_store_dword v136, v118, s[14:15] offset:512
	global_store_dword v136, v114, s[14:15] offset:576
	s_add_u32 s14, s14, 0x2000
	s_addc_u32 s15, s15, 0
	global_store_dword v136, v127, s[14:15]
	global_store_dword v136, v123, s[14:15] offset:64
	global_store_dword v136, v119, s[14:15] offset:512
	global_store_dword v136, v115, s[14:15] offset:576
	s_add_u32 s14, s14, 0x2000
	s_addc_u32 s15, s15, 0
	global_store_dword v136, v128, s[14:15]
	global_store_dword v136, v124, s[14:15] offset:64
	global_store_dword v136, v120, s[14:15] offset:512
	global_store_dword v136, v116, s[14:15] offset:576
	s_add_u32 s14, s14, 0x2000
	s_addc_u32 s15, s15, 0
	global_store_dword v136, v129, s[14:15]
	global_store_dword v136, v125, s[14:15] offset:64
	global_store_dword v136, v121, s[14:15] offset:512
	global_store_dword v136, v117, s[14:15] offset:576
	s_add_u32 s14, s14, 0x1a000
	s_addc_u32 s15, s15, 0
	global_load_dword v142, v136, s[100:101]
	global_load_dword v143, v136, s[100:101] offset:64
	global_load_dword v144, v136, s[100:101] offset:512
	global_load_dword v145, v136, s[100:101] offset:576
	s_add_u32 s100, s100, 0x2000
	s_addc_u32 s101, s101, 0
	global_load_dword v146, v136, s[100:101]
	global_load_dword v147, v136, s[100:101] offset:64
	global_load_dword v148, v136, s[100:101] offset:512
	global_load_dword v149, v136, s[100:101] offset:576
	s_add_u32 s100, s100, 0x2000
	s_addc_u32 s101, s101, 0
	global_load_dword v150, v136, s[100:101]
	global_load_dword v151, v136, s[100:101] offset:64
	global_load_dword v152, v136, s[100:101] offset:512
	global_load_dword v153, v136, s[100:101] offset:576
	s_add_u32 s100, s100, 0x2000
	s_addc_u32 s101, s101, 0
	global_load_dword v154, v136, s[100:101]
	global_load_dword v155, v136, s[100:101] offset:64
	global_load_dword v162, v136, s[100:101] offset:512
	global_load_dword v163, v136, s[100:101] offset:576
	s_add_u32 s100, s100, 0x1a000
	s_addc_u32 s101, s101, 0
	s_waitcnt vmcnt(32)
	v_fma_f32 v110, v110, v138, v164
	v_fma_f32 v106, v106, v139, v165
	v_fma_f32 v102, v102, v140, v166
	v_fma_f32 v98, v98, v141, v167
	v_fma_f32 v111, v111, v138, v168
	v_fma_f32 v107, v107, v139, v169
	v_fma_f32 v103, v103, v140, v176
	v_fma_f32 v99, v99, v141, v177
	v_fma_f32 v112, v112, v138, v178
	v_fma_f32 v108, v108, v139, v179
	v_fma_f32 v104, v104, v140, v180
	v_fma_f32 v100, v100, v141, v181
	v_fma_f32 v113, v113, v138, v182
	v_fma_f32 v109, v109, v139, v183
	v_fma_f32 v105, v105, v140, v184
	v_fma_f32 v101, v101, v141, v185
	global_store_dword v136, v110, s[14:15]
	global_store_dword v136, v106, s[14:15] offset:64
	global_store_dword v136, v102, s[14:15] offset:512
	global_store_dword v136, v98, s[14:15] offset:576
	s_add_u32 s14, s14, 0x2000
	s_addc_u32 s15, s15, 0
	global_store_dword v136, v111, s[14:15]
	global_store_dword v136, v107, s[14:15] offset:64
	global_store_dword v136, v103, s[14:15] offset:512
	global_store_dword v136, v99, s[14:15] offset:576
	s_add_u32 s14, s14, 0x2000
	s_addc_u32 s15, s15, 0
	global_store_dword v136, v112, s[14:15]
	global_store_dword v136, v108, s[14:15] offset:64
	global_store_dword v136, v104, s[14:15] offset:512
	global_store_dword v136, v100, s[14:15] offset:576
	s_add_u32 s14, s14, 0x2000
	s_addc_u32 s15, s15, 0
	global_store_dword v136, v113, s[14:15]
	global_store_dword v136, v109, s[14:15] offset:64
	global_store_dword v136, v105, s[14:15] offset:512
	global_store_dword v136, v101, s[14:15] offset:576
	s_add_u32 s14, s14, 0x1a000
	s_addc_u32 s15, s15, 0
	global_load_dword v164, v136, s[100:101]
	global_load_dword v165, v136, s[100:101] offset:64
	global_load_dword v166, v136, s[100:101] offset:512
	global_load_dword v167, v136, s[100:101] offset:576
	s_add_u32 s100, s100, 0x2000
	s_addc_u32 s101, s101, 0
	global_load_dword v168, v136, s[100:101]
	global_load_dword v169, v136, s[100:101] offset:64
	global_load_dword v176, v136, s[100:101] offset:512
	global_load_dword v177, v136, s[100:101] offset:576
	s_add_u32 s100, s100, 0x2000
	s_addc_u32 s101, s101, 0
	global_load_dword v178, v136, s[100:101]
	global_load_dword v179, v136, s[100:101] offset:64
	global_load_dword v180, v136, s[100:101] offset:512
	global_load_dword v181, v136, s[100:101] offset:576
	s_add_u32 s100, s100, 0x2000
	s_addc_u32 s101, s101, 0
	global_load_dword v182, v136, s[100:101]
	global_load_dword v183, v136, s[100:101] offset:64
	global_load_dword v184, v136, s[100:101] offset:512
	global_load_dword v185, v136, s[100:101] offset:576
	s_add_u32 s100, s100, 0x9a000
	s_addc_u32 s101, s101, 0
	s_waitcnt vmcnt(32)
;     __device__ __forceinline__ void operator()(const pg8::f32x4 (&acc)[2][2][4][2], const pg8::Unit& u, int wr, int wc, int fr, int fq) const {
;     ...
;         for (int ai = 0; ai < 2; ++ai)
; #pragma unroll
;             for (int m = 0; m < 4; ++m) { const size_t off = (size_t)(row0 + ai * 128 + m * 16) * D + col0;
; #pragma unroll
;                 for (int bj = 0; bj < 2; ++bj)
; #pragma unroll
;                     for (int n = 0; n < 2; ++n) { const pg8::f32x4 xv = *(const pg8::f32x4*)(xin + off + bj * 128 + n * 16);
;                         *(pg8::f32x4*)(xout + off + bj * 128 + n * 16) = xv + gv[bj][n] * acc[ai][bj][m][n]; }
;                 if (m & 1) asm volatile("" ::: "memory"); }
	v_fma_f32 v94, v94, v138, v142
	v_fma_f32 v90, v90, v139, v143
	v_fma_f32 v86, v86, v140, v144
	v_fma_f32 v82, v82, v141, v145
	v_fma_f32 v95, v95, v138, v146
	v_fma_f32 v91, v91, v139, v147
	v_fma_f32 v87, v87, v140, v148
	v_fma_f32 v83, v83, v141, v149
	v_fma_f32 v96, v96, v138, v150
	v_fma_f32 v92, v92, v139, v151
	v_fma_f32 v88, v88, v140, v152
	v_fma_f32 v84, v84, v141, v153
	v_fma_f32 v97, v97, v138, v154
	v_fma_f32 v93, v93, v139, v155
	v_fma_f32 v89, v89, v140, v162
	v_fma_f32 v85, v85, v141, v163
	global_store_dword v136, v94, s[14:15]
	global_store_dword v136, v90, s[14:15] offset:64
	global_store_dword v136, v86, s[14:15] offset:512
	global_store_dword v136, v82, s[14:15] offset:576
	s_add_u32 s14, s14, 0x2000
	s_addc_u32 s15, s15, 0
	global_store_dword v136, v95, s[14:15]
	global_store_dword v136, v91, s[14:15] offset:64
	global_store_dword v136, v87, s[14:15] offset:512
	global_store_dword v136, v83, s[14:15] offset:576
	s_add_u32 s14, s14, 0x2000
	s_addc_u32 s15, s15, 0
	global_store_dword v136, v96, s[14:15]
	global_store_dword v136, v92, s[14:15] offset:64
	global_store_dword v136, v88, s[14:15] offset:512
	global_store_dword v136, v84, s[14:15] offset:576
	s_add_u32 s14, s14, 0x2000
	s_addc_u32 s15, s15, 0
	global_store_dword v136, v97, s[14:15]
	global_store_dword v136, v93, s[14:15] offset:64
	global_store_dword v136, v89, s[14:15] offset:512
	global_store_dword v136, v85, s[14:15] offset:576
	s_add_u32 s14, s14, 0x1a000
	s_addc_u32 s15, s15, 0
	global_load_dword v142, v136, s[100:101]
	global_load_dword v143, v136, s[100:101] offset:64
	global_load_dword v144, v136, s[100:101] offset:512
	global_load_dword v145, v136, s[100:101] offset:576
	s_add_u32 s100, s100, 0x2000
	s_addc_u32 s101, s101, 0
	global_load_dword v146, v136, s[100:101]
	global_load_dword v147, v136, s[100:101] offset:64
	global_load_dword v148, v136, s[100:101] offset:512
	global_load_dword v149, v136, s[100:101] offset:576
	s_add_u32 s100, s100, 0x2000
	s_addc_u32 s101, s101, 0
	global_load_dword v150, v136, s[100:101]
	global_load_dword v151, v136, s[100:101] offset:64
	global_load_dword v152, v136, s[100:101] offset:512
	global_load_dword v153, v136, s[100:101] offset:576
	s_add_u32 s100, s100, 0x2000
	s_addc_u32 s101, s101, 0
	global_load_dword v154, v136, s[100:101]
	global_load_dword v155, v136, s[100:101] offset:64
	global_load_dword v162, v136, s[100:101] offset:512
	global_load_dword v163, v136, s[100:101] offset:576
	s_add_u32 s100, s100, 0x1a000
	s_addc_u32 s101, s101, 0
	s_waitcnt vmcnt(32)
	v_fma_f32 v78, v78, v138, v164
	v_fma_f32 v74, v74, v139, v165
	v_fma_f32 v70, v70, v140, v166
	v_fma_f32 v66, v66, v141, v167
	v_fma_f32 v79, v79, v138, v168
	v_fma_f32 v75, v75, v139, v169
	v_fma_f32 v71, v71, v140, v176
	v_fma_f32 v67, v67, v141, v177
	v_fma_f32 v80, v80, v138, v178
	v_fma_f32 v76, v76, v139, v179
	v_fma_f32 v72, v72, v140, v180
	v_fma_f32 v68, v68, v141, v181
	v_fma_f32 v81, v81, v138, v182
	v_fma_f32 v77, v77, v139, v183
	v_fma_f32 v73, v73, v140, v184
	v_fma_f32 v69, v69, v141, v185
	global_store_dword v136, v78, s[14:15]
	global_store_dword v136, v74, s[14:15] offset:64
	global_store_dword v136, v70, s[14:15] offset:512
	global_store_dword v136, v66, s[14:15] offset:576
	s_add_u32 s14, s14, 0x2000
	s_addc_u32 s15, s15, 0
	global_store_dword v136, v79, s[14:15]
	global_store_dword v136, v75, s[14:15] offset:64
	global_store_dword v136, v71, s[14:15] offset:512
	global_store_dword v136, v67, s[14:15] offset:576
	s_add_u32 s14, s14, 0x2000
	s_addc_u32 s15, s15, 0
	global_store_dword v136, v80, s[14:15]
	global_store_dword v136, v76, s[14:15] offset:64
	global_store_dword v136, v72, s[14:15] offset:512
	global_store_dword v136, v68, s[14:15] offset:576
	s_add_u32 s14, s14, 0x2000
	s_addc_u32 s15, s15, 0
	global_store_dword v136, v81, s[14:15]
	global_store_dword v136, v77, s[14:15] offset:64
	global_store_dword v136, v73, s[14:15] offset:512
	global_store_dword v136, v69, s[14:15] offset:576
	s_add_u32 s14, s14, 0x9a000
	s_addc_u32 s15, s15, 0
	global_load_dword v164, v136, s[100:101]
	global_load_dword v165, v136, s[100:101] offset:64
	global_load_dword v166, v136, s[100:101] offset:512
	global_load_dword v167, v136, s[100:101] offset:576
	s_add_u32 s100, s100, 0x2000
	s_addc_u32 s101, s101, 0
	global_load_dword v168, v136, s[100:101]
	global_load_dword v169, v136, s[100:101] offset:64
	global_load_dword v176, v136, s[100:101] offset:512
	global_load_dword v177, v136, s[100:101] offset:576
	s_add_u32 s100, s100, 0x2000
	s_addc_u32 s101, s101, 0
	global_load_dword v178, v136, s[100:101]
	global_load_dword v179, v136, s[100:101] offset:64
	global_load_dword v180, v136, s[100:101] offset:512
	global_load_dword v181, v136, s[100:101] offset:576
	s_add_u32 s100, s100, 0x2000
	s_addc_u32 s101, s101, 0
	global_load_dword v182, v136, s[100:101]
	global_load_dword v183, v136, s[100:101] offset:64
	global_load_dword v184, v136, s[100:101] offset:512
	global_load_dword v185, v136, s[100:101] offset:576
	s_add_u32 s100, s100, 0x1a000
	s_addc_u32 s101, s101, 0
	s_waitcnt vmcnt(32)
;     __device__ __forceinline__ void operator()(const pg8::f32x4 (&acc)[2][2][4][2], const pg8::Unit& u, int wr, int wc, int fr, int fq) const {
;     ...
;         for (int ai = 0; ai < 2; ++ai)
; #pragma unroll
;             for (int m = 0; m < 4; ++m) { const size_t off = (size_t)(row0 + ai * 128 + m * 16) * D + col0;
; #pragma unroll
;                 for (int bj = 0; bj < 2; ++bj)
; #pragma unroll
;                     for (int n = 0; n < 2; ++n) { const pg8::f32x4 xv = *(const pg8::f32x4*)(xin + off + bj * 128 + n * 16);
;                         *(pg8::f32x4*)(xout + off + bj * 128 + n * 16) = xv + gv[bj][n] * acc[ai][bj][m][n]; }
;                 if (m & 1) asm volatile("" ::: "memory"); }
	v_fma_f32 v62, v62, v138, v142
	v_fma_f32 v58, v58, v139, v143
	v_fma_f32 v54, v54, v140, v144
	v_fma_f32 v50, v50, v141, v145
	v_fma_f32 v63, v63, v138, v146
	v_fma_f32 v59, v59, v139, v147
	v_fma_f32 v55, v55, v140, v148
	v_fma_f32 v51, v51, v141, v149
	v_fma_f32 v64, v64, v138, v150
	v_fma_f32 v60, v60, v139, v151
	v_fma_f32 v56, v56, v140, v152
	v_fma_f32 v52, v52, v141, v153
	v_fma_f32 v65, v65, v138, v154
	v_fma_f32 v61, v61, v139, v155
	v_fma_f32 v57, v57, v140, v162
	v_fma_f32 v53, v53, v141, v163
	global_store_dword v136, v62, s[14:15]
	global_store_dword v136, v58, s[14:15] offset:64
	global_store_dword v136, v54, s[14:15] offset:512
	global_store_dword v136, v50, s[14:15] offset:576
	s_add_u32 s14, s14, 0x2000
	s_addc_u32 s15, s15, 0
	global_store_dword v136, v63, s[14:15]
	global_store_dword v136, v59, s[14:15] offset:64
	global_store_dword v136, v55, s[14:15] offset:512
	global_store_dword v136, v51, s[14:15] offset:576
	s_add_u32 s14, s14, 0x2000
	s_addc_u32 s15, s15, 0
	global_store_dword v136, v64, s[14:15]
	global_store_dword v136, v60, s[14:15] offset:64
	global_store_dword v136, v56, s[14:15] offset:512
	global_store_dword v136, v52, s[14:15] offset:576
	s_add_u32 s14, s14, 0x2000
	s_addc_u32 s15, s15, 0
	global_store_dword v136, v65, s[14:15]
	global_store_dword v136, v61, s[14:15] offset:64
	global_store_dword v136, v57, s[14:15] offset:512
	global_store_dword v136, v53, s[14:15] offset:576
	s_add_u32 s14, s14, 0x1a000
	s_addc_u32 s15, s15, 0
	global_load_dword v142, v136, s[100:101]
	global_load_dword v143, v136, s[100:101] offset:64
	global_load_dword v144, v136, s[100:101] offset:512
	global_load_dword v145, v136, s[100:101] offset:576
	s_add_u32 s100, s100, 0x2000
	s_addc_u32 s101, s101, 0
	global_load_dword v146, v136, s[100:101]
	global_load_dword v147, v136, s[100:101] offset:64
	global_load_dword v148, v136, s[100:101] offset:512
	global_load_dword v149, v136, s[100:101] offset:576
	s_add_u32 s100, s100, 0x2000
	s_addc_u32 s101, s101, 0
	global_load_dword v150, v136, s[100:101]
	global_load_dword v151, v136, s[100:101] offset:64
	global_load_dword v152, v136, s[100:101] offset:512
	global_load_dword v153, v136, s[100:101] offset:576
	s_add_u32 s100, s100, 0x2000
	s_addc_u32 s101, s101, 0
	global_load_dword v154, v136, s[100:101]
	global_load_dword v155, v136, s[100:101] offset:64
	global_load_dword v162, v136, s[100:101] offset:512
	global_load_dword v163, v136, s[100:101] offset:576
	s_add_u32 s100, s100, 0x1a000
	s_addc_u32 s101, s101, 0
	s_waitcnt vmcnt(32)
	v_fma_f32 v46, v46, v138, v164
	v_fma_f32 v42, v42, v139, v165
	v_fma_f32 v38, v38, v140, v166
	v_fma_f32 v34, v34, v141, v167
	v_fma_f32 v47, v47, v138, v168
	v_fma_f32 v43, v43, v139, v169
	v_fma_f32 v39, v39, v140, v176
	v_fma_f32 v35, v35, v141, v177
	v_fma_f32 v48, v48, v138, v178
	v_fma_f32 v44, v44, v139, v179
	v_fma_f32 v40, v40, v140, v180
	v_fma_f32 v36, v36, v141, v181
	v_fma_f32 v49, v49, v138, v182
	v_fma_f32 v45, v45, v139, v183
	v_fma_f32 v41, v41, v140, v184
	v_fma_f32 v37, v37, v141, v185
	global_store_dword v136, v46, s[14:15]
	global_store_dword v136, v42, s[14:15] offset:64
	global_store_dword v136, v38, s[14:15] offset:512
	global_store_dword v136, v34, s[14:15] offset:576
	s_add_u32 s14, s14, 0x2000
	s_addc_u32 s15, s15, 0
	global_store_dword v136, v47, s[14:15]
	global_store_dword v136, v43, s[14:15] offset:64
	global_store_dword v136, v39, s[14:15] offset:512
	global_store_dword v136, v35, s[14:15] offset:576
	s_add_u32 s14, s14, 0x2000
	s_addc_u32 s15, s15, 0
	global_store_dword v136, v48, s[14:15]
	global_store_dword v136, v44, s[14:15] offset:64
	global_store_dword v136, v40, s[14:15] offset:512
	global_store_dword v136, v36, s[14:15] offset:576
	s_add_u32 s14, s14, 0x2000
	s_addc_u32 s15, s15, 0
	global_store_dword v136, v49, s[14:15]
	global_store_dword v136, v45, s[14:15] offset:64
	global_store_dword v136, v41, s[14:15] offset:512
	global_store_dword v136, v37, s[14:15] offset:576
	s_add_u32 s14, s14, 0x1a000
	s_addc_u32 s15, s15, 0
	global_load_dword v164, v136, s[100:101]
	global_load_dword v165, v136, s[100:101] offset:64
	global_load_dword v166, v136, s[100:101] offset:512
	global_load_dword v167, v136, s[100:101] offset:576
	s_add_u32 s100, s100, 0x2000
	s_addc_u32 s101, s101, 0
	global_load_dword v168, v136, s[100:101]
	global_load_dword v169, v136, s[100:101] offset:64
	global_load_dword v176, v136, s[100:101] offset:512
	global_load_dword v177, v136, s[100:101] offset:576
	s_add_u32 s100, s100, 0x2000
	s_addc_u32 s101, s101, 0
	global_load_dword v178, v136, s[100:101]
	global_load_dword v179, v136, s[100:101] offset:64
	global_load_dword v180, v136, s[100:101] offset:512
	global_load_dword v181, v136, s[100:101] offset:576
	s_add_u32 s100, s100, 0x2000
	s_addc_u32 s101, s101, 0
	global_load_dword v182, v136, s[100:101]
	global_load_dword v183, v136, s[100:101] offset:64
	global_load_dword v184, v136, s[100:101] offset:512
	global_load_dword v185, v136, s[100:101] offset:576
	s_waitcnt vmcnt(32)
; #define PG8_BAR __builtin_amdgcn_s_barrier()
; template <class Epi, class Sched, bool ALIGN_EPI = false, bool SP2 = false>
; __device__ __forceinline__ void gemm_phase(PG8_LAS unsigned char* lds, const Gemm g, const Sched& S, const Epi& E, int wave_s) {
;     ...
;         if constexpr (ALIGN_EPI) { if (wr == 0) PG8_BAR; }
;         E(acc, cur, wr, wc, fr, fq); S.done(cur);
;         if (!has_next) break;
;     __device__ __forceinline__ void operator()(const pg8::f32x4 (&acc)[2][2][4][2], const pg8::Unit& u, int wr, int wc, int fr, int fq) const {
;     ...
;         for (int ai = 0; ai < 2; ++ai)
; #pragma unroll
;             for (int m = 0; m < 4; ++m) { const size_t off = (size_t)(row0 + ai * 128 + m * 16) * D + col0;
; #pragma unroll
;                 for (int bj = 0; bj < 2; ++bj)
; #pragma unroll
;                     for (int n = 0; n < 2; ++n) { const pg8::f32x4 xv = *(const pg8::f32x4*)(xin + off + bj * 128 + n * 16);
;                         *(pg8::f32x4*)(xout + off + bj * 128 + n * 16) = xv + gv[bj][n] * acc[ai][bj][m][n]; }
;                 if (m & 1) asm volatile("" ::: "memory"); }
	v_fma_f32 v30, v30, v138, v142
	v_fma_f32 v26, v26, v139, v143
	v_fma_f32 v22, v22, v140, v144
	v_fma_f32 v18, v18, v141, v145
	v_fma_f32 v31, v31, v138, v146
	v_fma_f32 v27, v27, v139, v147
	v_fma_f32 v23, v23, v140, v148
	v_fma_f32 v19, v19, v141, v149
	v_fma_f32 v32, v32, v138, v150
	v_fma_f32 v28, v28, v139, v151
	v_fma_f32 v24, v24, v140, v152
	v_fma_f32 v20, v20, v141, v153
	v_fma_f32 v33, v33, v138, v154
	v_fma_f32 v29, v29, v139, v155
	v_fma_f32 v25, v25, v140, v162
	v_fma_f32 v21, v21, v141, v163
	global_store_dword v136, v30, s[14:15]
	global_store_dword v136, v26, s[14:15] offset:64
	global_store_dword v136, v22, s[14:15] offset:512
	global_store_dword v136, v18, s[14:15] offset:576
	s_add_u32 s14, s14, 0x2000
	s_addc_u32 s15, s15, 0
	global_store_dword v136, v31, s[14:15]
	global_store_dword v136, v27, s[14:15] offset:64
	global_store_dword v136, v23, s[14:15] offset:512
	global_store_dword v136, v19, s[14:15] offset:576
	s_add_u32 s14, s14, 0x2000
	s_addc_u32 s15, s15, 0
	global_store_dword v136, v32, s[14:15]
	global_store_dword v136, v28, s[14:15] offset:64
	global_store_dword v136, v24, s[14:15] offset:512
	global_store_dword v136, v20, s[14:15] offset:576
	s_add_u32 s14, s14, 0x2000
	s_addc_u32 s15, s15, 0
	global_store_dword v136, v33, s[14:15]
	global_store_dword v136, v29, s[14:15] offset:64
	global_store_dword v136, v25, s[14:15] offset:512
	global_store_dword v136, v21, s[14:15] offset:576
	s_add_u32 s14, s14, 0x1a000
	s_addc_u32 s15, s15, 0
	s_waitcnt vmcnt(16)
	v_fma_f32 v14, v14, v138, v164
	v_fma_f32 v10, v10, v139, v165
	v_fma_f32 v6, v6, v140, v166
	v_fma_f32 v2, v2, v141, v167
	v_fma_f32 v15, v15, v138, v168
	v_fma_f32 v11, v11, v139, v169
	v_fma_f32 v7, v7, v140, v176
	v_fma_f32 v3, v3, v141, v177
	v_fma_f32 v16, v16, v138, v178
	v_fma_f32 v12, v12, v139, v179
	v_fma_f32 v8, v8, v140, v180
	v_fma_f32 v4, v4, v141, v181
	v_fma_f32 v17, v17, v138, v182
	v_fma_f32 v13, v13, v139, v183
	v_fma_f32 v9, v9, v140, v184
	v_fma_f32 v5, v5, v141, v185
	global_store_dword v136, v14, s[14:15]
	global_store_dword v136, v10, s[14:15] offset:64
	global_store_dword v136, v6, s[14:15] offset:512
	global_store_dword v136, v2, s[14:15] offset:576
	s_add_u32 s14, s14, 0x2000
	s_addc_u32 s15, s15, 0
	global_store_dword v136, v15, s[14:15]
	global_store_dword v136, v11, s[14:15] offset:64
	global_store_dword v136, v7, s[14:15] offset:512
	global_store_dword v136, v3, s[14:15] offset:576
	s_add_u32 s14, s14, 0x2000
	s_addc_u32 s15, s15, 0
	global_store_dword v136, v16, s[14:15]
	global_store_dword v136, v12, s[14:15] offset:64
	global_store_dword v136, v8, s[14:15] offset:512
	global_store_dword v136, v4, s[14:15] offset:576
	s_add_u32 s14, s14, 0x2000
	s_addc_u32 s15, s15, 0
	global_store_dword v136, v17, s[14:15]
	global_store_dword v136, v13, s[14:15] offset:64
	global_store_dword v136, v9, s[14:15] offset:512
	global_store_dword v136, v5, s[14:15] offset:576
	s_mov_b64 s[14:15], -1
	s_and_b64 vcc, exec, s[36:37]
	s_cbranch_vccnz .LBB0_1858
	s_andn2_b64 vcc, exec, s[0:1]
	s_cbranch_vccnz .LBB0_1857
	s_barrier
	s_branch .LBB0_1857
